# plus MLA k_rope tile epilogue: 16 rope table loads prefetched up front instead of load+vmcnt(0) per row behind 16 stores
# speedup vs baseline: 1.0032x; 1.0016x over previous
; DI bf16 f2bf(float a) { return (bf16)(pack2(a, 0.f) & 0xffffu); }
; DI int crow(int i, int g) { return (i & 3) + 8 * (i >> 2) + 4 * g; }
;     ...
;         const float2* t64 = (const float2*)(ws + OFF_TAB64);
;         bf16* Kb = (bf16*)(ws + OFF_K);
; #pragma unroll
;         for (int i = 0; i < 16; ++i) {
;           int s = s0 + crow(i, g);
;           float2 cs = t64[s * 32 + r];
;           float x1 = acc[0][i], x2 = acc[1][i];
;           bf16 o1 = f2bf(x1 * cs.x - x2 * cs.y), o2 = f2bf(x2 * cs.x + x1 * cs.y);
; #pragma unroll
;           for (int hh = 0; hh < 8; ++hh) {
;             bf16* kp = Kb + ((size_t)(bidx * 8 + hh) * 2048 + s) * 192 + 128;
;             kp[r] = o1; kp[32 + r] = o2;
;           }
;         }
.LBB0_235:
	s_and_b32 s0, s4, 0x780
	v_add_u32_e32 v66, s0, v144
	v_lshl_or_b32 v206, v66, 5, v128
	v_mov_b32_e32 v207, 0
	v_lshl_add_u64 v[206:207], v[206:207], 3, s[10:11]
	v_add_co_u32_e32 v208, vcc, 0x1000, v206
	s_nop 1
	v_addc_co_u32_e32 v209, vcc, 0, v207, vcc
	global_load_dwordx2 v[174:175], v[206:207], off
	global_load_dwordx2 v[176:177], v[206:207], off offset:256
	global_load_dwordx2 v[178:179], v[206:207], off offset:512
	global_load_dwordx2 v[180:181], v[206:207], off offset:768
	global_load_dwordx2 v[182:183], v[206:207], off offset:2048
	global_load_dwordx2 v[184:185], v[206:207], off offset:2304
	global_load_dwordx2 v[186:187], v[206:207], off offset:2560
	global_load_dwordx2 v[188:189], v[206:207], off offset:2816
	global_load_dwordx2 v[190:191], v[208:209], off
	global_load_dwordx2 v[192:193], v[208:209], off offset:256
	global_load_dwordx2 v[194:195], v[208:209], off offset:512
	global_load_dwordx2 v[196:197], v[208:209], off offset:768
	global_load_dwordx2 v[198:199], v[208:209], off offset:2048
	global_load_dwordx2 v[200:201], v[208:209], off offset:2304
	global_load_dwordx2 v[202:203], v[208:209], off offset:2560
	global_load_dwordx2 v[204:205], v[208:209], off offset:2816
	v_lshl_or_b32 v64, v66, 5, v128
	v_ashrrev_i32_e32 v65, 31, v64
	v_lshl_add_u64 v[64:65], v[64:65], 3, s[10:11]
	global_load_dwordx2 v[68:69], v[64:65], off
	s_ashr_i32 s5, s5, 1
	s_and_b32 s28, s5, -8
	s_ashr_i32 s29, s28, 31
	v_ashrrev_i32_e32 v67, 31, v66
	s_or_b32 s0, s28, 1
	s_lshl_b64 s[38:39], s[28:29], 11
	v_mov_b64_e32 v[64:65], s[22:23]
	s_or_b32 s18, s28, 2
	s_ashr_i32 s1, s0, 31
	v_lshl_add_u64 v[70:71], s[38:39], 0, v[66:67]
	s_ashr_i32 s19, s18, 31
	s_lshl_b64 s[34:35], s[0:1], 11
	v_mad_u64_u32 v[72:73], s[0:1], v70, s53, v[64:65]
	v_mov_b32_e32 v135, v131
	s_or_b32 s20, s28, 3
	s_lshl_b64 s[30:31], s[18:19], 11
	v_lshl_add_u64 v[74:75], s[34:35], 0, v[66:67]
	v_mad_i32_i24 v73, v71, s53, v73
	s_ashr_i32 s21, s20, 31
	v_lshl_add_u64 v[76:77], s[30:31], 0, v[66:67]
	v_mad_u64_u32 v[70:71], s[0:1], v74, s53, v[64:65]
	v_lshl_add_u64 v[72:73], v[72:73], 0, v[134:135]
	s_or_b32 s40, s28, 4
	s_lshl_b64 s[20:21], s[20:21], 11
	v_mad_u64_u32 v[82:83], s[0:1], v76, s53, v[64:65]
	v_mad_i32_i24 v71, v75, s53, v71
	v_lshl_add_u64 v[74:75], v[72:73], 0, s[12:13]
	v_add_co_u32_e32 v72, vcc, s54, v72
	s_ashr_i32 s41, s40, 31
	v_lshl_add_u64 v[78:79], s[20:21], 0, v[66:67]
	v_mad_i32_i24 v83, v77, s53, v83
	v_addc_co_u32_e32 v73, vcc, 0, v73, vcc
	v_lshl_add_u64 v[70:71], v[70:71], 0, v[134:135]
	s_lshl_b64 s[18:19], s[40:41], 11
	v_mad_u64_u32 v[84:85], s[0:1], v78, s53, v[64:65]
	v_lshl_add_u64 v[76:77], v[82:83], 0, v[134:135]
	v_lshl_add_u64 v[82:83], v[70:71], 0, s[12:13]
	v_add_co_u32_e32 v70, vcc, s54, v70
	v_lshl_add_u64 v[80:81], s[18:19], 0, v[66:67]
	v_mad_i32_i24 v85, v79, s53, v85
	v_addc_co_u32_e32 v71, vcc, 0, v71, vcc
	v_mad_u64_u32 v[86:87], s[0:1], v80, s53, v[64:65]
	v_lshl_add_u64 v[78:79], v[84:85], 0, v[134:135]
	v_lshl_add_u64 v[84:85], v[76:77], 0, s[12:13]
	v_add_co_u32_e32 v76, vcc, s54, v76
	v_mad_i32_i24 v87, v81, s53, v87
	s_nop 0
	v_addc_co_u32_e32 v77, vcc, 0, v77, vcc
	v_lshl_add_u64 v[80:81], v[86:87], 0, v[134:135]
	v_lshl_add_u64 v[86:87], v[78:79], 0, s[12:13]
	v_add_co_u32_e32 v78, vcc, s54, v78
	s_waitcnt vmcnt(8)
	v_lshl_add_u64 v[88:89], v[80:81], 0, s[12:13]
	v_addc_co_u32_e32 v79, vcc, 0, v79, vcc
	v_add_co_u32_e32 v80, vcc, s54, v80
	s_waitcnt vmcnt(0)
	v_mul_f32_e32 v90, v32, v69
	v_mul_f32_e32 v69, v48, v69
	v_fma_f32 v90, v48, v68, -v90
	v_fmac_f32_e32 v69, v32, v68
	v_cvt_pk_bf16_f32 v90, v90, s0
	v_cvt_pk_bf16_f32 v91, v69, s0
	s_or_b32 s0, s28, 5
	s_ashr_i32 s1, s0, 31
	s_lshl_b64 s[40:41], s[0:1], 11
	v_lshl_add_u64 v[68:69], s[40:41], 0, v[66:67]
	v_addc_co_u32_e32 v81, vcc, 0, v81, vcc
	global_store_short v[72:73], v90, off offset:256
	global_store_short v[74:75], v91, off offset:64
	global_store_short v[70:71], v90, off offset:256
	global_store_short v[82:83], v91, off offset:64
	global_store_short v[76:77], v90, off offset:256
	global_store_short v[84:85], v91, off offset:64
	global_store_short v[78:79], v90, off offset:256
	global_store_short v[86:87], v91, off offset:64
	global_store_short v[80:81], v90, off offset:256
	global_store_short v[88:89], v91, off offset:64
	v_mad_u64_u32 v[70:71], s[0:1], v68, s53, v[64:65]
	v_mad_i32_i24 v71, v69, s53, v71
	v_lshl_add_u64 v[68:69], v[70:71], 0, v[134:135]
	s_or_b32 s0, s28, 6
	v_lshl_add_u64 v[70:71], v[68:69], 0, s[12:13]
	v_add_co_u32_e32 v68, vcc, s54, v68
	s_ashr_i32 s1, s0, 31
	s_nop 0
	v_addc_co_u32_e32 v69, vcc, 0, v69, vcc
	s_lshl_b64 s[42:43], s[0:1], 11
	global_store_short v[68:69], v90, off offset:256
	global_store_short v[70:71], v91, off offset:64
	v_lshl_add_u64 v[68:69], s[42:43], 0, v[66:67]
	v_mad_u64_u32 v[70:71], s[0:1], v68, s53, v[64:65]
	v_mad_i32_i24 v71, v69, s53, v71
	v_lshl_add_u64 v[68:69], v[70:71], 0, v[134:135]
	s_or_b32 s0, s5, 7
	v_lshl_add_u64 v[70:71], v[68:69], 0, s[12:13]
	v_add_co_u32_e32 v68, vcc, s54, v68
	s_ashr_i32 s1, s0, 31
	s_nop 0
	v_addc_co_u32_e32 v69, vcc, 0, v69, vcc
	s_lshl_b64 s[44:45], s[0:1], 11
	global_store_short v[68:69], v90, off offset:256
	global_store_short v[70:71], v91, off offset:64
	v_lshl_add_u64 v[68:69], s[44:45], 0, v[66:67]
	v_mad_u64_u32 v[70:71], s[0:1], v68, s53, v[64:65]
	v_mad_i32_i24 v71, v69, s53, v71
	v_lshl_add_u64 v[68:69], v[70:71], 0, v[134:135]
	v_lshl_add_u64 v[70:71], v[68:69], 0, s[12:13]
	v_add_co_u32_e32 v68, vcc, s54, v68
	s_nop 1
	v_addc_co_u32_e32 v69, vcc, 0, v69, vcc
	global_store_short v[68:69], v90, off offset:256
	global_store_short v[70:71], v91, off offset:64
; DI bf16 f2bf(float a) { return (bf16)(pack2(a, 0.f) & 0xffffu); }
; DI int crow(int i, int g) { return (i & 3) + 8 * (i >> 2) + 4 * g; }
;     ...
;         const float2* t64 = (const float2*)(ws + OFF_TAB64);
;         bf16* Kb = (bf16*)(ws + OFF_K);
; #pragma unroll
;         for (int i = 0; i < 16; ++i) {
;           int s = s0 + crow(i, g);
;           float2 cs = t64[s * 32 + r];
;           float x1 = acc[0][i], x2 = acc[1][i];
;           bf16 o1 = f2bf(x1 * cs.x - x2 * cs.y), o2 = f2bf(x2 * cs.x + x1 * cs.y);
; #pragma unroll
;           for (int hh = 0; hh < 8; ++hh) {
;             bf16* kp = Kb + ((size_t)(bidx * 8 + hh) * 2048 + s) * 192 + 128;
;             kp[r] = o1; kp[32 + r] = o2;
;           }
;         }
	v_or_b32_e32 v68, 1, v66
	v_lshl_or_b32 v70, v68, 5, v128
	v_ashrrev_i32_e32 v71, 31, v70
	v_lshl_add_u64 v[70:71], v[70:71], 3, s[10:11]
	v_mov_b32_e32 v70, v176
	v_mov_b32_e32 v71, v177
	v_ashrrev_i32_e32 v69, 31, v68
	v_lshl_add_u64 v[72:73], s[38:39], 0, v[68:69]
	v_mad_u64_u32 v[74:75], s[0:1], v72, s53, v[64:65]
	v_lshl_add_u64 v[76:77], s[34:35], 0, v[68:69]
	v_mad_i32_i24 v75, v73, s53, v75
	v_mad_u64_u32 v[72:73], s[0:1], v76, s53, v[64:65]
	v_lshl_add_u64 v[74:75], v[74:75], 0, v[134:135]
	v_lshl_add_u64 v[78:79], s[30:31], 0, v[68:69]
	v_mad_i32_i24 v73, v77, s53, v73
	v_lshl_add_u64 v[76:77], v[74:75], 0, s[12:13]
	v_add_co_u32_e32 v74, vcc, s54, v74
	v_lshl_add_u64 v[72:73], v[72:73], 0, v[134:135]
	s_nop 0
	v_addc_co_u32_e32 v75, vcc, 0, v75, vcc
	v_lshl_add_u64 v[80:81], v[72:73], 0, s[12:13]
	v_add_co_u32_e32 v72, vcc, s54, v72
	v_mul_f32_e32 v67, v33, v71
	v_mul_f32_e32 v71, v49, v71
	v_fma_f32 v67, v49, v70, -v67
	v_fmac_f32_e32 v71, v33, v70
	v_cvt_pk_bf16_f32 v67, v67, s0
	v_cvt_pk_bf16_f32 v82, v71, s0
	v_mad_u64_u32 v[70:71], s[0:1], v78, s53, v[64:65]
	v_mad_i32_i24 v71, v79, s53, v71
	v_addc_co_u32_e32 v73, vcc, 0, v73, vcc
	v_lshl_add_u64 v[70:71], v[70:71], 0, v[134:135]
	global_store_short v[74:75], v67, off offset:256
	global_store_short v[76:77], v82, off offset:64
	global_store_short v[72:73], v67, off offset:256
	global_store_short v[80:81], v82, off offset:64
	v_lshl_add_u64 v[72:73], v[70:71], 0, s[12:13]
	v_add_co_u32_e32 v70, vcc, s54, v70
	s_nop 1
	v_addc_co_u32_e32 v71, vcc, 0, v71, vcc
	global_store_short v[70:71], v67, off offset:256
	global_store_short v[72:73], v82, off offset:64
	v_lshl_add_u64 v[70:71], s[20:21], 0, v[68:69]
	v_mad_u64_u32 v[72:73], s[0:1], v70, s53, v[64:65]
	v_mad_i32_i24 v73, v71, s53, v73
	v_lshl_add_u64 v[70:71], v[72:73], 0, v[134:135]
	v_lshl_add_u64 v[72:73], v[70:71], 0, s[12:13]
	v_add_co_u32_e32 v70, vcc, s54, v70
	s_nop 1
	v_addc_co_u32_e32 v71, vcc, 0, v71, vcc
	global_store_short v[70:71], v67, off offset:256
	global_store_short v[72:73], v82, off offset:64
	v_lshl_add_u64 v[70:71], s[18:19], 0, v[68:69]
	v_mad_u64_u32 v[72:73], s[0:1], v70, s53, v[64:65]
	v_mad_i32_i24 v73, v71, s53, v73
	v_lshl_add_u64 v[70:71], v[72:73], 0, v[134:135]
	v_lshl_add_u64 v[72:73], v[70:71], 0, s[12:13]
	v_add_co_u32_e32 v70, vcc, s54, v70
	s_nop 1
	v_addc_co_u32_e32 v71, vcc, 0, v71, vcc
	global_store_short v[70:71], v67, off offset:256
	global_store_short v[72:73], v82, off offset:64
	v_lshl_add_u64 v[70:71], s[40:41], 0, v[68:69]
	v_mad_u64_u32 v[72:73], s[0:1], v70, s53, v[64:65]
	v_mad_i32_i24 v73, v71, s53, v73
	v_lshl_add_u64 v[70:71], v[72:73], 0, v[134:135]
	v_lshl_add_u64 v[72:73], v[70:71], 0, s[12:13]
	v_add_co_u32_e32 v70, vcc, s54, v70
	s_nop 1
	v_addc_co_u32_e32 v71, vcc, 0, v71, vcc
	global_store_short v[70:71], v67, off offset:256
	global_store_short v[72:73], v82, off offset:64
	v_lshl_add_u64 v[70:71], s[42:43], 0, v[68:69]
	v_mad_u64_u32 v[72:73], s[0:1], v70, s53, v[64:65]
	v_mad_i32_i24 v73, v71, s53, v73
	v_lshl_add_u64 v[70:71], v[72:73], 0, v[134:135]
	v_lshl_add_u64 v[72:73], v[70:71], 0, s[12:13]
	v_add_co_u32_e32 v70, vcc, s54, v70
	v_lshl_add_u64 v[68:69], s[44:45], 0, v[68:69]
	s_nop 0
	v_addc_co_u32_e32 v71, vcc, 0, v71, vcc
	global_store_short v[70:71], v67, off offset:256
	global_store_short v[72:73], v82, off offset:64
	v_mad_u64_u32 v[70:71], s[0:1], v68, s53, v[64:65]
	v_mad_i32_i24 v71, v69, s53, v71
	v_lshl_add_u64 v[68:69], v[70:71], 0, v[134:135]
	v_lshl_add_u64 v[70:71], v[68:69], 0, s[12:13]
	v_add_co_u32_e32 v68, vcc, s54, v68
	s_nop 1
	v_addc_co_u32_e32 v69, vcc, 0, v69, vcc
	global_store_short v[68:69], v67, off offset:256
	global_store_short v[70:71], v82, off offset:64
	v_or_b32_e32 v68, 2, v66
	v_lshl_or_b32 v70, v68, 5, v128
	v_ashrrev_i32_e32 v71, 31, v70
	v_lshl_add_u64 v[70:71], v[70:71], 3, s[10:11]
	v_mov_b32_e32 v70, v178
	v_mov_b32_e32 v71, v179
	v_ashrrev_i32_e32 v69, 31, v68
	v_mul_f32_e32 v67, v34, v71
	v_mul_f32_e32 v71, v50, v71
	v_fmac_f32_e32 v71, v34, v70
	v_fma_f32 v67, v50, v70, -v67
	v_cvt_pk_bf16_f32 v74, v71, s0
	v_lshl_add_u64 v[70:71], s[38:39], 0, v[68:69]
	v_cvt_pk_bf16_f32 v67, v67, s0
	v_mad_u64_u32 v[72:73], s[0:1], v70, s53, v[64:65]
	v_mad_i32_i24 v73, v71, s53, v73
	v_lshl_add_u64 v[70:71], v[72:73], 0, v[134:135]
	v_lshl_add_u64 v[72:73], v[70:71], 0, s[12:13]
	v_add_co_u32_e32 v70, vcc, s54, v70
	s_nop 1
	v_addc_co_u32_e32 v71, vcc, 0, v71, vcc
	global_store_short v[70:71], v67, off offset:256
	global_store_short v[72:73], v74, off offset:64
	v_lshl_add_u64 v[70:71], s[34:35], 0, v[68:69]
	v_mad_u64_u32 v[72:73], s[0:1], v70, s53, v[64:65]
	v_mad_i32_i24 v73, v71, s53, v73
	v_lshl_add_u64 v[70:71], v[72:73], 0, v[134:135]
	v_lshl_add_u64 v[72:73], v[70:71], 0, s[12:13]
	v_add_co_u32_e32 v70, vcc, s54, v70
	s_nop 1
	v_addc_co_u32_e32 v71, vcc, 0, v71, vcc
	global_store_short v[70:71], v67, off offset:256
	global_store_short v[72:73], v74, off offset:64
	v_lshl_add_u64 v[70:71], s[30:31], 0, v[68:69]
	v_mad_u64_u32 v[72:73], s[0:1], v70, s53, v[64:65]
	v_mad_i32_i24 v73, v71, s53, v73
	v_lshl_add_u64 v[70:71], v[72:73], 0, v[134:135]
	v_lshl_add_u64 v[72:73], v[70:71], 0, s[12:13]
	v_add_co_u32_e32 v70, vcc, s54, v70
	s_nop 1
	v_addc_co_u32_e32 v71, vcc, 0, v71, vcc
	global_store_short v[70:71], v67, off offset:256
	global_store_short v[72:73], v74, off offset:64
	v_lshl_add_u64 v[70:71], s[20:21], 0, v[68:69]
	v_mad_u64_u32 v[72:73], s[0:1], v70, s53, v[64:65]
	v_mad_i32_i24 v73, v71, s53, v73
	v_lshl_add_u64 v[70:71], v[72:73], 0, v[134:135]
	v_lshl_add_u64 v[72:73], v[70:71], 0, s[12:13]
; DI bf16 f2bf(float a) { return (bf16)(pack2(a, 0.f) & 0xffffu); }
; DI int crow(int i, int g) { return (i & 3) + 8 * (i >> 2) + 4 * g; }
;     ...
;         const float2* t64 = (const float2*)(ws + OFF_TAB64);
;         bf16* Kb = (bf16*)(ws + OFF_K);
; #pragma unroll
;         for (int i = 0; i < 16; ++i) {
;           int s = s0 + crow(i, g);
;           float2 cs = t64[s * 32 + r];
;           float x1 = acc[0][i], x2 = acc[1][i];
;           bf16 o1 = f2bf(x1 * cs.x - x2 * cs.y), o2 = f2bf(x2 * cs.x + x1 * cs.y);
; #pragma unroll
;           for (int hh = 0; hh < 8; ++hh) {
;             bf16* kp = Kb + ((size_t)(bidx * 8 + hh) * 2048 + s) * 192 + 128;
;             kp[r] = o1; kp[32 + r] = o2;
;           }
;         }
	v_add_co_u32_e32 v70, vcc, s54, v70
	s_nop 1
	v_addc_co_u32_e32 v71, vcc, 0, v71, vcc
	global_store_short v[70:71], v67, off offset:256
	global_store_short v[72:73], v74, off offset:64
	v_lshl_add_u64 v[70:71], s[18:19], 0, v[68:69]
	v_mad_u64_u32 v[72:73], s[0:1], v70, s53, v[64:65]
	v_mad_i32_i24 v73, v71, s53, v73
	v_lshl_add_u64 v[70:71], v[72:73], 0, v[134:135]
	v_lshl_add_u64 v[72:73], v[70:71], 0, s[12:13]
	v_add_co_u32_e32 v70, vcc, s54, v70
	s_nop 1
	v_addc_co_u32_e32 v71, vcc, 0, v71, vcc
	global_store_short v[70:71], v67, off offset:256
	global_store_short v[72:73], v74, off offset:64
	v_lshl_add_u64 v[70:71], s[40:41], 0, v[68:69]
	v_mad_u64_u32 v[72:73], s[0:1], v70, s53, v[64:65]
	v_mad_i32_i24 v73, v71, s53, v73
	v_lshl_add_u64 v[70:71], v[72:73], 0, v[134:135]
	v_lshl_add_u64 v[72:73], v[70:71], 0, s[12:13]
	v_add_co_u32_e32 v70, vcc, s54, v70
	s_nop 1
	v_addc_co_u32_e32 v71, vcc, 0, v71, vcc
	global_store_short v[70:71], v67, off offset:256
	global_store_short v[72:73], v74, off offset:64
	v_lshl_add_u64 v[70:71], s[42:43], 0, v[68:69]
	v_mad_u64_u32 v[72:73], s[0:1], v70, s53, v[64:65]
	v_mad_i32_i24 v73, v71, s53, v73
	v_lshl_add_u64 v[70:71], v[72:73], 0, v[134:135]
	v_lshl_add_u64 v[72:73], v[70:71], 0, s[12:13]
	v_add_co_u32_e32 v70, vcc, s54, v70
	v_lshl_add_u64 v[68:69], s[44:45], 0, v[68:69]
	s_nop 0
	v_addc_co_u32_e32 v71, vcc, 0, v71, vcc
	global_store_short v[70:71], v67, off offset:256
	global_store_short v[72:73], v74, off offset:64
	v_mad_u64_u32 v[70:71], s[0:1], v68, s53, v[64:65]
	v_mad_i32_i24 v71, v69, s53, v71
	v_lshl_add_u64 v[68:69], v[70:71], 0, v[134:135]
	v_lshl_add_u64 v[70:71], v[68:69], 0, s[12:13]
	v_add_co_u32_e32 v68, vcc, s54, v68
	s_nop 1
	v_addc_co_u32_e32 v69, vcc, 0, v69, vcc
	global_store_short v[68:69], v67, off offset:256
	global_store_short v[70:71], v74, off offset:64
	v_or_b32_e32 v68, 3, v66
	v_lshl_or_b32 v70, v68, 5, v128
	v_ashrrev_i32_e32 v71, 31, v70
	v_lshl_add_u64 v[70:71], v[70:71], 3, s[10:11]
	v_mov_b32_e32 v70, v180
	v_mov_b32_e32 v71, v181
	v_mul_f32_e32 v69, v51, v71
	v_fmac_f32_e32 v69, v35, v70
	v_mul_f32_e32 v67, v35, v71
	v_cvt_pk_bf16_f32 v74, v69, s0
	v_ashrrev_i32_e32 v69, 31, v68
	v_fma_f32 v67, v51, v70, -v67
	v_lshl_add_u64 v[70:71], s[38:39], 0, v[68:69]
	v_cvt_pk_bf16_f32 v67, v67, s0
	v_mad_u64_u32 v[72:73], s[0:1], v70, s53, v[64:65]
	v_mad_i32_i24 v73, v71, s53, v73
	v_lshl_add_u64 v[70:71], v[72:73], 0, v[134:135]
	v_lshl_add_u64 v[72:73], v[70:71], 0, s[12:13]
	v_add_co_u32_e32 v70, vcc, s54, v70
	s_nop 1
	v_addc_co_u32_e32 v71, vcc, 0, v71, vcc
	global_store_short v[70:71], v67, off offset:256
	global_store_short v[72:73], v74, off offset:64
	v_lshl_add_u64 v[70:71], s[34:35], 0, v[68:69]
	v_mad_u64_u32 v[72:73], s[0:1], v70, s53, v[64:65]
	v_mad_i32_i24 v73, v71, s53, v73
	v_lshl_add_u64 v[70:71], v[72:73], 0, v[134:135]
	v_lshl_add_u64 v[72:73], v[70:71], 0, s[12:13]
	v_add_co_u32_e32 v70, vcc, s54, v70
	s_nop 1
	v_addc_co_u32_e32 v71, vcc, 0, v71, vcc
	global_store_short v[70:71], v67, off offset:256
	global_store_short v[72:73], v74, off offset:64
	v_lshl_add_u64 v[70:71], s[30:31], 0, v[68:69]
	v_mad_u64_u32 v[72:73], s[0:1], v70, s53, v[64:65]
	v_mad_i32_i24 v73, v71, s53, v73
	v_lshl_add_u64 v[70:71], v[72:73], 0, v[134:135]
	v_lshl_add_u64 v[72:73], v[70:71], 0, s[12:13]
	v_add_co_u32_e32 v70, vcc, s54, v70
	s_nop 1
	v_addc_co_u32_e32 v71, vcc, 0, v71, vcc
	global_store_short v[70:71], v67, off offset:256
	global_store_short v[72:73], v74, off offset:64
	v_lshl_add_u64 v[70:71], s[20:21], 0, v[68:69]
	v_mad_u64_u32 v[72:73], s[0:1], v70, s53, v[64:65]
	v_mad_i32_i24 v73, v71, s53, v73
	v_lshl_add_u64 v[70:71], v[72:73], 0, v[134:135]
	v_lshl_add_u64 v[72:73], v[70:71], 0, s[12:13]
	v_add_co_u32_e32 v70, vcc, s54, v70
	s_nop 1
	v_addc_co_u32_e32 v71, vcc, 0, v71, vcc
	global_store_short v[70:71], v67, off offset:256
	global_store_short v[72:73], v74, off offset:64
	v_lshl_add_u64 v[70:71], s[18:19], 0, v[68:69]
	v_mad_u64_u32 v[72:73], s[0:1], v70, s53, v[64:65]
	v_mad_i32_i24 v73, v71, s53, v73
	v_lshl_add_u64 v[70:71], v[72:73], 0, v[134:135]
	v_lshl_add_u64 v[72:73], v[70:71], 0, s[12:13]
	v_add_co_u32_e32 v70, vcc, s54, v70
	s_nop 1
	v_addc_co_u32_e32 v71, vcc, 0, v71, vcc
	global_store_short v[70:71], v67, off offset:256
	global_store_short v[72:73], v74, off offset:64
	v_lshl_add_u64 v[70:71], s[40:41], 0, v[68:69]
	v_mad_u64_u32 v[72:73], s[0:1], v70, s53, v[64:65]
	v_mad_i32_i24 v73, v71, s53, v73
	v_lshl_add_u64 v[70:71], v[72:73], 0, v[134:135]
	v_lshl_add_u64 v[72:73], v[70:71], 0, s[12:13]
	v_add_co_u32_e32 v70, vcc, s54, v70
	s_nop 1
	v_addc_co_u32_e32 v71, vcc, 0, v71, vcc
	global_store_short v[70:71], v67, off offset:256
	global_store_short v[72:73], v74, off offset:64
	v_lshl_add_u64 v[70:71], s[42:43], 0, v[68:69]
	v_mad_u64_u32 v[72:73], s[0:1], v70, s53, v[64:65]
	v_mad_i32_i24 v73, v71, s53, v73
	v_lshl_add_u64 v[70:71], v[72:73], 0, v[134:135]
	v_lshl_add_u64 v[72:73], v[70:71], 0, s[12:13]
	v_add_co_u32_e32 v70, vcc, s54, v70
	v_lshl_add_u64 v[68:69], s[44:45], 0, v[68:69]
	s_nop 0
	v_addc_co_u32_e32 v71, vcc, 0, v71, vcc
	global_store_short v[70:71], v67, off offset:256
	global_store_short v[72:73], v74, off offset:64
	v_mad_u64_u32 v[70:71], s[0:1], v68, s53, v[64:65]
	v_mad_i32_i24 v71, v69, s53, v71
	v_lshl_add_u64 v[68:69], v[70:71], 0, v[134:135]
	v_lshl_add_u64 v[70:71], v[68:69], 0, s[12:13]
	v_add_co_u32_e32 v68, vcc, s54, v68
	s_nop 1
	v_addc_co_u32_e32 v69, vcc, 0, v69, vcc
	global_store_short v[68:69], v67, off offset:256
	global_store_short v[70:71], v74, off offset:64
	v_or_b32_e32 v68, 8, v66
; DI bf16 f2bf(float a) { return (bf16)(pack2(a, 0.f) & 0xffffu); }
; DI int crow(int i, int g) { return (i & 3) + 8 * (i >> 2) + 4 * g; }
;     ...
;         const float2* t64 = (const float2*)(ws + OFF_TAB64);
;         bf16* Kb = (bf16*)(ws + OFF_K);
; #pragma unroll
;         for (int i = 0; i < 16; ++i) {
;           int s = s0 + crow(i, g);
;           float2 cs = t64[s * 32 + r];
;           float x1 = acc[0][i], x2 = acc[1][i];
;           bf16 o1 = f2bf(x1 * cs.x - x2 * cs.y), o2 = f2bf(x2 * cs.x + x1 * cs.y);
; #pragma unroll
;           for (int hh = 0; hh < 8; ++hh) {
;             bf16* kp = Kb + ((size_t)(bidx * 8 + hh) * 2048 + s) * 192 + 128;
;             kp[r] = o1; kp[32 + r] = o2;
;           }
;         }
	v_lshl_or_b32 v70, v68, 5, v128
	v_ashrrev_i32_e32 v71, 31, v70
	v_lshl_add_u64 v[70:71], v[70:71], 3, s[10:11]
	v_mov_b32_e32 v70, v182
	v_mov_b32_e32 v71, v183
	v_mul_f32_e32 v69, v52, v71
	v_fmac_f32_e32 v69, v36, v70
	v_mul_f32_e32 v67, v36, v71
	v_cvt_pk_bf16_f32 v74, v69, s0
	v_ashrrev_i32_e32 v69, 31, v68
	v_fma_f32 v67, v52, v70, -v67
	v_lshl_add_u64 v[70:71], s[38:39], 0, v[68:69]
	v_cvt_pk_bf16_f32 v67, v67, s0
	v_mad_u64_u32 v[72:73], s[0:1], v70, s53, v[64:65]
	v_mad_i32_i24 v73, v71, s53, v73
	v_lshl_add_u64 v[70:71], v[72:73], 0, v[134:135]
	v_lshl_add_u64 v[72:73], v[70:71], 0, s[12:13]
	v_add_co_u32_e32 v70, vcc, s54, v70
	s_nop 1
	v_addc_co_u32_e32 v71, vcc, 0, v71, vcc
	global_store_short v[70:71], v67, off offset:256
	global_store_short v[72:73], v74, off offset:64
	v_lshl_add_u64 v[70:71], s[34:35], 0, v[68:69]
	v_mad_u64_u32 v[72:73], s[0:1], v70, s53, v[64:65]
	v_mad_i32_i24 v73, v71, s53, v73
	v_lshl_add_u64 v[70:71], v[72:73], 0, v[134:135]
	v_lshl_add_u64 v[72:73], v[70:71], 0, s[12:13]
	v_add_co_u32_e32 v70, vcc, s54, v70
	s_nop 1
	v_addc_co_u32_e32 v71, vcc, 0, v71, vcc
	global_store_short v[70:71], v67, off offset:256
	global_store_short v[72:73], v74, off offset:64
	v_lshl_add_u64 v[70:71], s[30:31], 0, v[68:69]
	v_mad_u64_u32 v[72:73], s[0:1], v70, s53, v[64:65]
	v_mad_i32_i24 v73, v71, s53, v73
	v_lshl_add_u64 v[70:71], v[72:73], 0, v[134:135]
	v_lshl_add_u64 v[72:73], v[70:71], 0, s[12:13]
	v_add_co_u32_e32 v70, vcc, s54, v70
	s_nop 1
	v_addc_co_u32_e32 v71, vcc, 0, v71, vcc
	global_store_short v[70:71], v67, off offset:256
	global_store_short v[72:73], v74, off offset:64
	v_lshl_add_u64 v[70:71], s[20:21], 0, v[68:69]
	v_mad_u64_u32 v[72:73], s[0:1], v70, s53, v[64:65]
	v_mad_i32_i24 v73, v71, s53, v73
	v_lshl_add_u64 v[70:71], v[72:73], 0, v[134:135]
	v_lshl_add_u64 v[72:73], v[70:71], 0, s[12:13]
	v_add_co_u32_e32 v70, vcc, s54, v70
	s_nop 1
	v_addc_co_u32_e32 v71, vcc, 0, v71, vcc
	global_store_short v[70:71], v67, off offset:256
	global_store_short v[72:73], v74, off offset:64
	v_lshl_add_u64 v[70:71], s[18:19], 0, v[68:69]
	v_mad_u64_u32 v[72:73], s[0:1], v70, s53, v[64:65]
	v_mad_i32_i24 v73, v71, s53, v73
	v_lshl_add_u64 v[70:71], v[72:73], 0, v[134:135]
	v_lshl_add_u64 v[72:73], v[70:71], 0, s[12:13]
	v_add_co_u32_e32 v70, vcc, s54, v70
	s_nop 1
	v_addc_co_u32_e32 v71, vcc, 0, v71, vcc
	global_store_short v[70:71], v67, off offset:256
	global_store_short v[72:73], v74, off offset:64
	v_lshl_add_u64 v[70:71], s[40:41], 0, v[68:69]
	v_mad_u64_u32 v[72:73], s[0:1], v70, s53, v[64:65]
	v_mad_i32_i24 v73, v71, s53, v73
	v_lshl_add_u64 v[70:71], v[72:73], 0, v[134:135]
	v_lshl_add_u64 v[72:73], v[70:71], 0, s[12:13]
	v_add_co_u32_e32 v70, vcc, s54, v70
	s_nop 1
	v_addc_co_u32_e32 v71, vcc, 0, v71, vcc
	global_store_short v[70:71], v67, off offset:256
	global_store_short v[72:73], v74, off offset:64
	v_lshl_add_u64 v[70:71], s[42:43], 0, v[68:69]
	v_mad_u64_u32 v[72:73], s[0:1], v70, s53, v[64:65]
	v_mad_i32_i24 v73, v71, s53, v73
	v_lshl_add_u64 v[70:71], v[72:73], 0, v[134:135]
	v_lshl_add_u64 v[72:73], v[70:71], 0, s[12:13]
	v_add_co_u32_e32 v70, vcc, s54, v70
	v_lshl_add_u64 v[68:69], s[44:45], 0, v[68:69]
	s_nop 0
	v_addc_co_u32_e32 v71, vcc, 0, v71, vcc
	global_store_short v[70:71], v67, off offset:256
	global_store_short v[72:73], v74, off offset:64
	v_mad_u64_u32 v[70:71], s[0:1], v68, s53, v[64:65]
	v_mad_i32_i24 v71, v69, s53, v71
	v_lshl_add_u64 v[68:69], v[70:71], 0, v[134:135]
	v_lshl_add_u64 v[70:71], v[68:69], 0, s[12:13]
	v_add_co_u32_e32 v68, vcc, s54, v68
	s_nop 1
	v_addc_co_u32_e32 v69, vcc, 0, v69, vcc
	global_store_short v[68:69], v67, off offset:256
	global_store_short v[70:71], v74, off offset:64
	v_or_b32_e32 v68, 9, v66
	v_lshl_or_b32 v70, v68, 5, v128
	v_ashrrev_i32_e32 v71, 31, v70
	v_lshl_add_u64 v[70:71], v[70:71], 3, s[10:11]
	v_mov_b32_e32 v70, v184
	v_mov_b32_e32 v71, v185
	v_mul_f32_e32 v69, v53, v71
	v_fmac_f32_e32 v69, v37, v70
	v_mul_f32_e32 v67, v37, v71
	v_cvt_pk_bf16_f32 v74, v69, s0
	v_ashrrev_i32_e32 v69, 31, v68
	v_fma_f32 v67, v53, v70, -v67
	v_lshl_add_u64 v[70:71], s[38:39], 0, v[68:69]
	v_cvt_pk_bf16_f32 v67, v67, s0
	v_mad_u64_u32 v[72:73], s[0:1], v70, s53, v[64:65]
	v_mad_i32_i24 v73, v71, s53, v73
	v_lshl_add_u64 v[70:71], v[72:73], 0, v[134:135]
	v_lshl_add_u64 v[72:73], v[70:71], 0, s[12:13]
	v_add_co_u32_e32 v70, vcc, s54, v70
	s_nop 1
	v_addc_co_u32_e32 v71, vcc, 0, v71, vcc
	global_store_short v[70:71], v67, off offset:256
	global_store_short v[72:73], v74, off offset:64
	v_lshl_add_u64 v[70:71], s[34:35], 0, v[68:69]
	v_mad_u64_u32 v[72:73], s[0:1], v70, s53, v[64:65]
	v_mad_i32_i24 v73, v71, s53, v73
	v_lshl_add_u64 v[70:71], v[72:73], 0, v[134:135]
	v_lshl_add_u64 v[72:73], v[70:71], 0, s[12:13]
	v_add_co_u32_e32 v70, vcc, s54, v70
	s_nop 1
	v_addc_co_u32_e32 v71, vcc, 0, v71, vcc
	global_store_short v[70:71], v67, off offset:256
	global_store_short v[72:73], v74, off offset:64
	v_lshl_add_u64 v[70:71], s[30:31], 0, v[68:69]
	v_mad_u64_u32 v[72:73], s[0:1], v70, s53, v[64:65]
	v_mad_i32_i24 v73, v71, s53, v73
	v_lshl_add_u64 v[70:71], v[72:73], 0, v[134:135]
	v_lshl_add_u64 v[72:73], v[70:71], 0, s[12:13]
	v_add_co_u32_e32 v70, vcc, s54, v70
	s_nop 1
	v_addc_co_u32_e32 v71, vcc, 0, v71, vcc
	global_store_short v[70:71], v67, off offset:256
	global_store_short v[72:73], v74, off offset:64
	v_lshl_add_u64 v[70:71], s[20:21], 0, v[68:69]
	v_mad_u64_u32 v[72:73], s[0:1], v70, s53, v[64:65]
	v_mad_i32_i24 v73, v71, s53, v73
	v_lshl_add_u64 v[70:71], v[72:73], 0, v[134:135]
	v_lshl_add_u64 v[72:73], v[70:71], 0, s[12:13]
	v_add_co_u32_e32 v70, vcc, s54, v70
; DI bf16 f2bf(float a) { return (bf16)(pack2(a, 0.f) & 0xffffu); }
; DI int crow(int i, int g) { return (i & 3) + 8 * (i >> 2) + 4 * g; }
;     ...
;         const float2* t64 = (const float2*)(ws + OFF_TAB64);
;         bf16* Kb = (bf16*)(ws + OFF_K);
; #pragma unroll
;         for (int i = 0; i < 16; ++i) {
;           int s = s0 + crow(i, g);
;           float2 cs = t64[s * 32 + r];
;           float x1 = acc[0][i], x2 = acc[1][i];
;           bf16 o1 = f2bf(x1 * cs.x - x2 * cs.y), o2 = f2bf(x2 * cs.x + x1 * cs.y);
; #pragma unroll
;           for (int hh = 0; hh < 8; ++hh) {
;             bf16* kp = Kb + ((size_t)(bidx * 8 + hh) * 2048 + s) * 192 + 128;
;             kp[r] = o1; kp[32 + r] = o2;
;           }
;         }
	s_nop 1
	v_addc_co_u32_e32 v71, vcc, 0, v71, vcc
	global_store_short v[70:71], v67, off offset:256
	global_store_short v[72:73], v74, off offset:64
	v_lshl_add_u64 v[70:71], s[18:19], 0, v[68:69]
	v_mad_u64_u32 v[72:73], s[0:1], v70, s53, v[64:65]
	v_mad_i32_i24 v73, v71, s53, v73
	v_lshl_add_u64 v[70:71], v[72:73], 0, v[134:135]
	v_lshl_add_u64 v[72:73], v[70:71], 0, s[12:13]
	v_add_co_u32_e32 v70, vcc, s54, v70
	s_nop 1
	v_addc_co_u32_e32 v71, vcc, 0, v71, vcc
	global_store_short v[70:71], v67, off offset:256
	global_store_short v[72:73], v74, off offset:64
	v_lshl_add_u64 v[70:71], s[40:41], 0, v[68:69]
	v_mad_u64_u32 v[72:73], s[0:1], v70, s53, v[64:65]
	v_mad_i32_i24 v73, v71, s53, v73
	v_lshl_add_u64 v[70:71], v[72:73], 0, v[134:135]
	v_lshl_add_u64 v[72:73], v[70:71], 0, s[12:13]
	v_add_co_u32_e32 v70, vcc, s54, v70
	s_nop 1
	v_addc_co_u32_e32 v71, vcc, 0, v71, vcc
	global_store_short v[70:71], v67, off offset:256
	global_store_short v[72:73], v74, off offset:64
	v_lshl_add_u64 v[70:71], s[42:43], 0, v[68:69]
	v_mad_u64_u32 v[72:73], s[0:1], v70, s53, v[64:65]
	v_mad_i32_i24 v73, v71, s53, v73
	v_lshl_add_u64 v[70:71], v[72:73], 0, v[134:135]
	v_lshl_add_u64 v[72:73], v[70:71], 0, s[12:13]
	v_add_co_u32_e32 v70, vcc, s54, v70
	v_lshl_add_u64 v[68:69], s[44:45], 0, v[68:69]
	s_nop 0
	v_addc_co_u32_e32 v71, vcc, 0, v71, vcc
	global_store_short v[70:71], v67, off offset:256
	global_store_short v[72:73], v74, off offset:64
	v_mad_u64_u32 v[70:71], s[0:1], v68, s53, v[64:65]
	v_mad_i32_i24 v71, v69, s53, v71
	v_lshl_add_u64 v[68:69], v[70:71], 0, v[134:135]
	v_lshl_add_u64 v[70:71], v[68:69], 0, s[12:13]
	v_add_co_u32_e32 v68, vcc, s54, v68
	s_nop 1
	v_addc_co_u32_e32 v69, vcc, 0, v69, vcc
	global_store_short v[68:69], v67, off offset:256
	global_store_short v[70:71], v74, off offset:64
	v_or_b32_e32 v68, 10, v66
	v_lshl_or_b32 v70, v68, 5, v128
	v_ashrrev_i32_e32 v71, 31, v70
	v_lshl_add_u64 v[70:71], v[70:71], 3, s[10:11]
	v_mov_b32_e32 v70, v186
	v_mov_b32_e32 v71, v187
	v_mul_f32_e32 v69, v54, v71
	v_fmac_f32_e32 v69, v38, v70
	v_mul_f32_e32 v67, v38, v71
	v_cvt_pk_bf16_f32 v74, v69, s0
	v_ashrrev_i32_e32 v69, 31, v68
	v_fma_f32 v67, v54, v70, -v67
	v_lshl_add_u64 v[70:71], s[38:39], 0, v[68:69]
	v_cvt_pk_bf16_f32 v67, v67, s0
	v_mad_u64_u32 v[72:73], s[0:1], v70, s53, v[64:65]
	v_mad_i32_i24 v73, v71, s53, v73
	v_lshl_add_u64 v[70:71], v[72:73], 0, v[134:135]
	v_lshl_add_u64 v[72:73], v[70:71], 0, s[12:13]
	v_add_co_u32_e32 v70, vcc, s54, v70
	s_nop 1
	v_addc_co_u32_e32 v71, vcc, 0, v71, vcc
	global_store_short v[70:71], v67, off offset:256
	global_store_short v[72:73], v74, off offset:64
	v_lshl_add_u64 v[70:71], s[34:35], 0, v[68:69]
	v_mad_u64_u32 v[72:73], s[0:1], v70, s53, v[64:65]
	v_mad_i32_i24 v73, v71, s53, v73
	v_lshl_add_u64 v[70:71], v[72:73], 0, v[134:135]
	v_lshl_add_u64 v[72:73], v[70:71], 0, s[12:13]
	v_add_co_u32_e32 v70, vcc, s54, v70
	s_nop 1
	v_addc_co_u32_e32 v71, vcc, 0, v71, vcc
	global_store_short v[70:71], v67, off offset:256
	global_store_short v[72:73], v74, off offset:64
	v_lshl_add_u64 v[70:71], s[30:31], 0, v[68:69]
	v_mad_u64_u32 v[72:73], s[0:1], v70, s53, v[64:65]
	v_mad_i32_i24 v73, v71, s53, v73
	v_lshl_add_u64 v[70:71], v[72:73], 0, v[134:135]
	v_lshl_add_u64 v[72:73], v[70:71], 0, s[12:13]
	v_add_co_u32_e32 v70, vcc, s54, v70
	s_nop 1
	v_addc_co_u32_e32 v71, vcc, 0, v71, vcc
	global_store_short v[70:71], v67, off offset:256
	global_store_short v[72:73], v74, off offset:64
	v_lshl_add_u64 v[70:71], s[20:21], 0, v[68:69]
	v_mad_u64_u32 v[72:73], s[0:1], v70, s53, v[64:65]
	v_mad_i32_i24 v73, v71, s53, v73
	v_lshl_add_u64 v[70:71], v[72:73], 0, v[134:135]
	v_lshl_add_u64 v[72:73], v[70:71], 0, s[12:13]
	v_add_co_u32_e32 v70, vcc, s54, v70
	s_nop 1
	v_addc_co_u32_e32 v71, vcc, 0, v71, vcc
	global_store_short v[70:71], v67, off offset:256
	global_store_short v[72:73], v74, off offset:64
	v_lshl_add_u64 v[70:71], s[18:19], 0, v[68:69]
	v_mad_u64_u32 v[72:73], s[0:1], v70, s53, v[64:65]
	v_mad_i32_i24 v73, v71, s53, v73
	v_lshl_add_u64 v[70:71], v[72:73], 0, v[134:135]
	v_lshl_add_u64 v[72:73], v[70:71], 0, s[12:13]
	v_add_co_u32_e32 v70, vcc, s54, v70
	s_nop 1
	v_addc_co_u32_e32 v71, vcc, 0, v71, vcc
	global_store_short v[70:71], v67, off offset:256
	global_store_short v[72:73], v74, off offset:64
	v_lshl_add_u64 v[70:71], s[40:41], 0, v[68:69]
	v_mad_u64_u32 v[72:73], s[0:1], v70, s53, v[64:65]
	v_mad_i32_i24 v73, v71, s53, v73
	v_lshl_add_u64 v[70:71], v[72:73], 0, v[134:135]
	v_lshl_add_u64 v[72:73], v[70:71], 0, s[12:13]
	v_add_co_u32_e32 v70, vcc, s54, v70
	s_nop 1
	v_addc_co_u32_e32 v71, vcc, 0, v71, vcc
	global_store_short v[70:71], v67, off offset:256
	global_store_short v[72:73], v74, off offset:64
	v_lshl_add_u64 v[70:71], s[42:43], 0, v[68:69]
	v_mad_u64_u32 v[72:73], s[0:1], v70, s53, v[64:65]
	v_mad_i32_i24 v73, v71, s53, v73
	v_lshl_add_u64 v[70:71], v[72:73], 0, v[134:135]
	v_lshl_add_u64 v[72:73], v[70:71], 0, s[12:13]
	v_add_co_u32_e32 v70, vcc, s54, v70
	v_lshl_add_u64 v[68:69], s[44:45], 0, v[68:69]
	s_nop 0
	v_addc_co_u32_e32 v71, vcc, 0, v71, vcc
	global_store_short v[70:71], v67, off offset:256
	global_store_short v[72:73], v74, off offset:64
	v_mad_u64_u32 v[70:71], s[0:1], v68, s53, v[64:65]
	v_mad_i32_i24 v71, v69, s53, v71
	v_lshl_add_u64 v[68:69], v[70:71], 0, v[134:135]
	v_lshl_add_u64 v[70:71], v[68:69], 0, s[12:13]
	v_add_co_u32_e32 v68, vcc, s54, v68
	s_nop 1
	v_addc_co_u32_e32 v69, vcc, 0, v69, vcc
	global_store_short v[68:69], v67, off offset:256
	global_store_short v[70:71], v74, off offset:64
	v_or_b32_e32 v68, 11, v66
	v_lshl_or_b32 v70, v68, 5, v128
; DI bf16 f2bf(float a) { return (bf16)(pack2(a, 0.f) & 0xffffu); }
; DI int crow(int i, int g) { return (i & 3) + 8 * (i >> 2) + 4 * g; }
;     ...
;         const float2* t64 = (const float2*)(ws + OFF_TAB64);
;         bf16* Kb = (bf16*)(ws + OFF_K);
; #pragma unroll
;         for (int i = 0; i < 16; ++i) {
;           int s = s0 + crow(i, g);
;           float2 cs = t64[s * 32 + r];
;           float x1 = acc[0][i], x2 = acc[1][i];
;           bf16 o1 = f2bf(x1 * cs.x - x2 * cs.y), o2 = f2bf(x2 * cs.x + x1 * cs.y);
; #pragma unroll
;           for (int hh = 0; hh < 8; ++hh) {
;             bf16* kp = Kb + ((size_t)(bidx * 8 + hh) * 2048 + s) * 192 + 128;
;             kp[r] = o1; kp[32 + r] = o2;
;           }
;         }
	v_ashrrev_i32_e32 v71, 31, v70
	v_lshl_add_u64 v[70:71], v[70:71], 3, s[10:11]
	v_mov_b32_e32 v70, v188
	v_mov_b32_e32 v71, v189
	v_mul_f32_e32 v69, v55, v71
	v_fmac_f32_e32 v69, v39, v70
	v_mul_f32_e32 v67, v39, v71
	v_cvt_pk_bf16_f32 v74, v69, s0
	v_ashrrev_i32_e32 v69, 31, v68
	v_fma_f32 v67, v55, v70, -v67
	v_lshl_add_u64 v[70:71], s[38:39], 0, v[68:69]
	v_cvt_pk_bf16_f32 v67, v67, s0
	v_mad_u64_u32 v[72:73], s[0:1], v70, s53, v[64:65]
	v_mad_i32_i24 v73, v71, s53, v73
	v_lshl_add_u64 v[70:71], v[72:73], 0, v[134:135]
	v_lshl_add_u64 v[72:73], v[70:71], 0, s[12:13]
	v_add_co_u32_e32 v70, vcc, s54, v70
	s_nop 1
	v_addc_co_u32_e32 v71, vcc, 0, v71, vcc
	global_store_short v[70:71], v67, off offset:256
	global_store_short v[72:73], v74, off offset:64
	v_lshl_add_u64 v[70:71], s[34:35], 0, v[68:69]
	v_mad_u64_u32 v[72:73], s[0:1], v70, s53, v[64:65]
	v_mad_i32_i24 v73, v71, s53, v73
	v_lshl_add_u64 v[70:71], v[72:73], 0, v[134:135]
	v_lshl_add_u64 v[72:73], v[70:71], 0, s[12:13]
	v_add_co_u32_e32 v70, vcc, s54, v70
	s_nop 1
	v_addc_co_u32_e32 v71, vcc, 0, v71, vcc
	global_store_short v[70:71], v67, off offset:256
	global_store_short v[72:73], v74, off offset:64
	v_lshl_add_u64 v[70:71], s[30:31], 0, v[68:69]
	v_mad_u64_u32 v[72:73], s[0:1], v70, s53, v[64:65]
	v_mad_i32_i24 v73, v71, s53, v73
	v_lshl_add_u64 v[70:71], v[72:73], 0, v[134:135]
	v_lshl_add_u64 v[72:73], v[70:71], 0, s[12:13]
	v_add_co_u32_e32 v70, vcc, s54, v70
	s_nop 1
	v_addc_co_u32_e32 v71, vcc, 0, v71, vcc
	global_store_short v[70:71], v67, off offset:256
	global_store_short v[72:73], v74, off offset:64
	v_lshl_add_u64 v[70:71], s[20:21], 0, v[68:69]
	v_mad_u64_u32 v[72:73], s[0:1], v70, s53, v[64:65]
	v_mad_i32_i24 v73, v71, s53, v73
	v_lshl_add_u64 v[70:71], v[72:73], 0, v[134:135]
	v_lshl_add_u64 v[72:73], v[70:71], 0, s[12:13]
	v_add_co_u32_e32 v70, vcc, s54, v70
	s_nop 1
	v_addc_co_u32_e32 v71, vcc, 0, v71, vcc
	global_store_short v[70:71], v67, off offset:256
	global_store_short v[72:73], v74, off offset:64
	v_lshl_add_u64 v[70:71], s[18:19], 0, v[68:69]
	v_mad_u64_u32 v[72:73], s[0:1], v70, s53, v[64:65]
	v_mad_i32_i24 v73, v71, s53, v73
	v_lshl_add_u64 v[70:71], v[72:73], 0, v[134:135]
	v_lshl_add_u64 v[72:73], v[70:71], 0, s[12:13]
	v_add_co_u32_e32 v70, vcc, s54, v70
	s_nop 1
	v_addc_co_u32_e32 v71, vcc, 0, v71, vcc
	global_store_short v[70:71], v67, off offset:256
	global_store_short v[72:73], v74, off offset:64
	v_lshl_add_u64 v[70:71], s[40:41], 0, v[68:69]
	v_mad_u64_u32 v[72:73], s[0:1], v70, s53, v[64:65]
	v_mad_i32_i24 v73, v71, s53, v73
	v_lshl_add_u64 v[70:71], v[72:73], 0, v[134:135]
	v_lshl_add_u64 v[72:73], v[70:71], 0, s[12:13]
	v_add_co_u32_e32 v70, vcc, s54, v70
	s_nop 1
	v_addc_co_u32_e32 v71, vcc, 0, v71, vcc
	global_store_short v[70:71], v67, off offset:256
	global_store_short v[72:73], v74, off offset:64
	v_lshl_add_u64 v[70:71], s[42:43], 0, v[68:69]
	v_mad_u64_u32 v[72:73], s[0:1], v70, s53, v[64:65]
	v_mad_i32_i24 v73, v71, s53, v73
	v_lshl_add_u64 v[70:71], v[72:73], 0, v[134:135]
	v_lshl_add_u64 v[72:73], v[70:71], 0, s[12:13]
	v_add_co_u32_e32 v70, vcc, s54, v70
	v_lshl_add_u64 v[68:69], s[44:45], 0, v[68:69]
	s_nop 0
	v_addc_co_u32_e32 v71, vcc, 0, v71, vcc
	global_store_short v[70:71], v67, off offset:256
	global_store_short v[72:73], v74, off offset:64
	v_mad_u64_u32 v[70:71], s[0:1], v68, s53, v[64:65]
	v_mad_i32_i24 v71, v69, s53, v71
	v_lshl_add_u64 v[68:69], v[70:71], 0, v[134:135]
	v_lshl_add_u64 v[70:71], v[68:69], 0, s[12:13]
	v_add_co_u32_e32 v68, vcc, s54, v68
	s_nop 1
	v_addc_co_u32_e32 v69, vcc, 0, v69, vcc
	global_store_short v[68:69], v67, off offset:256
	global_store_short v[70:71], v74, off offset:64
	v_or_b32_e32 v68, 16, v66
	v_lshl_or_b32 v70, v68, 5, v128
	v_ashrrev_i32_e32 v71, 31, v70
	v_lshl_add_u64 v[70:71], v[70:71], 3, s[10:11]
	v_mov_b32_e32 v70, v190
	v_mov_b32_e32 v71, v191
	v_mul_f32_e32 v69, v56, v71
	v_fmac_f32_e32 v69, v40, v70
	v_mul_f32_e32 v67, v40, v71
	v_cvt_pk_bf16_f32 v74, v69, s0
	v_ashrrev_i32_e32 v69, 31, v68
	v_fma_f32 v67, v56, v70, -v67
	v_lshl_add_u64 v[70:71], s[38:39], 0, v[68:69]
	v_cvt_pk_bf16_f32 v67, v67, s0
	v_mad_u64_u32 v[72:73], s[0:1], v70, s53, v[64:65]
	v_mad_i32_i24 v73, v71, s53, v73
	v_lshl_add_u64 v[70:71], v[72:73], 0, v[134:135]
	v_lshl_add_u64 v[72:73], v[70:71], 0, s[12:13]
	v_add_co_u32_e32 v70, vcc, s54, v70
	s_nop 1
	v_addc_co_u32_e32 v71, vcc, 0, v71, vcc
	global_store_short v[70:71], v67, off offset:256
	global_store_short v[72:73], v74, off offset:64
	v_lshl_add_u64 v[70:71], s[34:35], 0, v[68:69]
	v_mad_u64_u32 v[72:73], s[0:1], v70, s53, v[64:65]
	v_mad_i32_i24 v73, v71, s53, v73
	v_lshl_add_u64 v[70:71], v[72:73], 0, v[134:135]
	v_lshl_add_u64 v[72:73], v[70:71], 0, s[12:13]
	v_add_co_u32_e32 v70, vcc, s54, v70
	s_nop 1
	v_addc_co_u32_e32 v71, vcc, 0, v71, vcc
	global_store_short v[70:71], v67, off offset:256
	global_store_short v[72:73], v74, off offset:64
	v_lshl_add_u64 v[70:71], s[30:31], 0, v[68:69]
	v_mad_u64_u32 v[72:73], s[0:1], v70, s53, v[64:65]
	v_mad_i32_i24 v73, v71, s53, v73
	v_lshl_add_u64 v[70:71], v[72:73], 0, v[134:135]
	v_lshl_add_u64 v[72:73], v[70:71], 0, s[12:13]
	v_add_co_u32_e32 v70, vcc, s54, v70
	s_nop 1
	v_addc_co_u32_e32 v71, vcc, 0, v71, vcc
	global_store_short v[70:71], v67, off offset:256
	global_store_short v[72:73], v74, off offset:64
	v_lshl_add_u64 v[70:71], s[20:21], 0, v[68:69]
	v_mad_u64_u32 v[72:73], s[0:1], v70, s53, v[64:65]
	v_mad_i32_i24 v73, v71, s53, v73
	v_lshl_add_u64 v[70:71], v[72:73], 0, v[134:135]
	v_lshl_add_u64 v[72:73], v[70:71], 0, s[12:13]
	v_add_co_u32_e32 v70, vcc, s54, v70
	s_nop 1
; DI bf16 f2bf(float a) { return (bf16)(pack2(a, 0.f) & 0xffffu); }
; DI int crow(int i, int g) { return (i & 3) + 8 * (i >> 2) + 4 * g; }
;     ...
;         const float2* t64 = (const float2*)(ws + OFF_TAB64);
;         bf16* Kb = (bf16*)(ws + OFF_K);
; #pragma unroll
;         for (int i = 0; i < 16; ++i) {
;           int s = s0 + crow(i, g);
;           float2 cs = t64[s * 32 + r];
;           float x1 = acc[0][i], x2 = acc[1][i];
;           bf16 o1 = f2bf(x1 * cs.x - x2 * cs.y), o2 = f2bf(x2 * cs.x + x1 * cs.y);
; #pragma unroll
;           for (int hh = 0; hh < 8; ++hh) {
;             bf16* kp = Kb + ((size_t)(bidx * 8 + hh) * 2048 + s) * 192 + 128;
;             kp[r] = o1; kp[32 + r] = o2;
;           }
;         }
	v_addc_co_u32_e32 v71, vcc, 0, v71, vcc
	global_store_short v[70:71], v67, off offset:256
	global_store_short v[72:73], v74, off offset:64
	v_lshl_add_u64 v[70:71], s[18:19], 0, v[68:69]
	v_mad_u64_u32 v[72:73], s[0:1], v70, s53, v[64:65]
	v_mad_i32_i24 v73, v71, s53, v73
	v_lshl_add_u64 v[70:71], v[72:73], 0, v[134:135]
	v_lshl_add_u64 v[72:73], v[70:71], 0, s[12:13]
	v_add_co_u32_e32 v70, vcc, s54, v70
	s_nop 1
	v_addc_co_u32_e32 v71, vcc, 0, v71, vcc
	global_store_short v[70:71], v67, off offset:256
	global_store_short v[72:73], v74, off offset:64
	v_lshl_add_u64 v[70:71], s[40:41], 0, v[68:69]
	v_mad_u64_u32 v[72:73], s[0:1], v70, s53, v[64:65]
	v_mad_i32_i24 v73, v71, s53, v73
	v_lshl_add_u64 v[70:71], v[72:73], 0, v[134:135]
	v_lshl_add_u64 v[72:73], v[70:71], 0, s[12:13]
	v_add_co_u32_e32 v70, vcc, s54, v70
	s_nop 1
	v_addc_co_u32_e32 v71, vcc, 0, v71, vcc
	global_store_short v[70:71], v67, off offset:256
	global_store_short v[72:73], v74, off offset:64
	v_lshl_add_u64 v[70:71], s[42:43], 0, v[68:69]
	v_mad_u64_u32 v[72:73], s[0:1], v70, s53, v[64:65]
	v_mad_i32_i24 v73, v71, s53, v73
	v_lshl_add_u64 v[70:71], v[72:73], 0, v[134:135]
	v_lshl_add_u64 v[72:73], v[70:71], 0, s[12:13]
	v_add_co_u32_e32 v70, vcc, s54, v70
	v_lshl_add_u64 v[68:69], s[44:45], 0, v[68:69]
	s_nop 0
	v_addc_co_u32_e32 v71, vcc, 0, v71, vcc
	global_store_short v[70:71], v67, off offset:256
	global_store_short v[72:73], v74, off offset:64
	v_mad_u64_u32 v[70:71], s[0:1], v68, s53, v[64:65]
	v_mad_i32_i24 v71, v69, s53, v71
	v_lshl_add_u64 v[68:69], v[70:71], 0, v[134:135]
	v_lshl_add_u64 v[70:71], v[68:69], 0, s[12:13]
	v_add_co_u32_e32 v68, vcc, s54, v68
	s_nop 1
	v_addc_co_u32_e32 v69, vcc, 0, v69, vcc
	global_store_short v[68:69], v67, off offset:256
	global_store_short v[70:71], v74, off offset:64
	v_or_b32_e32 v68, 17, v66
	v_lshl_or_b32 v70, v68, 5, v128
	v_ashrrev_i32_e32 v71, 31, v70
	v_lshl_add_u64 v[70:71], v[70:71], 3, s[10:11]
	v_mov_b32_e32 v70, v192
	v_mov_b32_e32 v71, v193
	v_mul_f32_e32 v69, v57, v71
	v_fmac_f32_e32 v69, v41, v70
	v_mul_f32_e32 v67, v41, v71
	v_cvt_pk_bf16_f32 v74, v69, s0
	v_ashrrev_i32_e32 v69, 31, v68
	v_fma_f32 v67, v57, v70, -v67
	v_lshl_add_u64 v[70:71], s[38:39], 0, v[68:69]
	v_cvt_pk_bf16_f32 v67, v67, s0
	v_mad_u64_u32 v[72:73], s[0:1], v70, s53, v[64:65]
	v_mad_i32_i24 v73, v71, s53, v73
	v_lshl_add_u64 v[70:71], v[72:73], 0, v[134:135]
	v_lshl_add_u64 v[72:73], v[70:71], 0, s[12:13]
	v_add_co_u32_e32 v70, vcc, s54, v70
	s_nop 1
	v_addc_co_u32_e32 v71, vcc, 0, v71, vcc
	global_store_short v[70:71], v67, off offset:256
	global_store_short v[72:73], v74, off offset:64
	v_lshl_add_u64 v[70:71], s[34:35], 0, v[68:69]
	v_mad_u64_u32 v[72:73], s[0:1], v70, s53, v[64:65]
	v_mad_i32_i24 v73, v71, s53, v73
	v_lshl_add_u64 v[70:71], v[72:73], 0, v[134:135]
	v_lshl_add_u64 v[72:73], v[70:71], 0, s[12:13]
	v_add_co_u32_e32 v70, vcc, s54, v70
	s_nop 1
	v_addc_co_u32_e32 v71, vcc, 0, v71, vcc
	global_store_short v[70:71], v67, off offset:256
	global_store_short v[72:73], v74, off offset:64
	v_lshl_add_u64 v[70:71], s[30:31], 0, v[68:69]
	v_mad_u64_u32 v[72:73], s[0:1], v70, s53, v[64:65]
	v_mad_i32_i24 v73, v71, s53, v73
	v_lshl_add_u64 v[70:71], v[72:73], 0, v[134:135]
	v_lshl_add_u64 v[72:73], v[70:71], 0, s[12:13]
	v_add_co_u32_e32 v70, vcc, s54, v70
	s_nop 1
	v_addc_co_u32_e32 v71, vcc, 0, v71, vcc
	global_store_short v[70:71], v67, off offset:256
	global_store_short v[72:73], v74, off offset:64
	v_lshl_add_u64 v[70:71], s[20:21], 0, v[68:69]
	v_mad_u64_u32 v[72:73], s[0:1], v70, s53, v[64:65]
	v_mad_i32_i24 v73, v71, s53, v73
	v_lshl_add_u64 v[70:71], v[72:73], 0, v[134:135]
	v_lshl_add_u64 v[72:73], v[70:71], 0, s[12:13]
	v_add_co_u32_e32 v70, vcc, s54, v70
	s_nop 1
	v_addc_co_u32_e32 v71, vcc, 0, v71, vcc
	global_store_short v[70:71], v67, off offset:256
	global_store_short v[72:73], v74, off offset:64
	v_lshl_add_u64 v[70:71], s[18:19], 0, v[68:69]
	v_mad_u64_u32 v[72:73], s[0:1], v70, s53, v[64:65]
	v_mad_i32_i24 v73, v71, s53, v73
	v_lshl_add_u64 v[70:71], v[72:73], 0, v[134:135]
	v_lshl_add_u64 v[72:73], v[70:71], 0, s[12:13]
	v_add_co_u32_e32 v70, vcc, s54, v70
	s_nop 1
	v_addc_co_u32_e32 v71, vcc, 0, v71, vcc
	global_store_short v[70:71], v67, off offset:256
	global_store_short v[72:73], v74, off offset:64
	v_lshl_add_u64 v[70:71], s[40:41], 0, v[68:69]
	v_mad_u64_u32 v[72:73], s[0:1], v70, s53, v[64:65]
	v_mad_i32_i24 v73, v71, s53, v73
	v_lshl_add_u64 v[70:71], v[72:73], 0, v[134:135]
	v_lshl_add_u64 v[72:73], v[70:71], 0, s[12:13]
	v_add_co_u32_e32 v70, vcc, s54, v70
	s_nop 1
	v_addc_co_u32_e32 v71, vcc, 0, v71, vcc
	global_store_short v[70:71], v67, off offset:256
	global_store_short v[72:73], v74, off offset:64
	v_lshl_add_u64 v[70:71], s[42:43], 0, v[68:69]
	v_mad_u64_u32 v[72:73], s[0:1], v70, s53, v[64:65]
	v_mad_i32_i24 v73, v71, s53, v73
	v_lshl_add_u64 v[70:71], v[72:73], 0, v[134:135]
	v_lshl_add_u64 v[72:73], v[70:71], 0, s[12:13]
	v_add_co_u32_e32 v70, vcc, s54, v70
	v_lshl_add_u64 v[68:69], s[44:45], 0, v[68:69]
	s_nop 0
	v_addc_co_u32_e32 v71, vcc, 0, v71, vcc
	global_store_short v[70:71], v67, off offset:256
	global_store_short v[72:73], v74, off offset:64
	v_mad_u64_u32 v[70:71], s[0:1], v68, s53, v[64:65]
	v_mad_i32_i24 v71, v69, s53, v71
	v_lshl_add_u64 v[68:69], v[70:71], 0, v[134:135]
	v_lshl_add_u64 v[70:71], v[68:69], 0, s[12:13]
	v_add_co_u32_e32 v68, vcc, s54, v68
	s_nop 1
	v_addc_co_u32_e32 v69, vcc, 0, v69, vcc
	global_store_short v[68:69], v67, off offset:256
	global_store_short v[70:71], v74, off offset:64
	v_or_b32_e32 v68, 18, v66
	v_lshl_or_b32 v70, v68, 5, v128
	v_ashrrev_i32_e32 v71, 31, v70
; DI bf16 f2bf(float a) { return (bf16)(pack2(a, 0.f) & 0xffffu); }
; DI int crow(int i, int g) { return (i & 3) + 8 * (i >> 2) + 4 * g; }
;     ...
;         const float2* t64 = (const float2*)(ws + OFF_TAB64);
;         bf16* Kb = (bf16*)(ws + OFF_K);
; #pragma unroll
;         for (int i = 0; i < 16; ++i) {
;           int s = s0 + crow(i, g);
;           float2 cs = t64[s * 32 + r];
;           float x1 = acc[0][i], x2 = acc[1][i];
;           bf16 o1 = f2bf(x1 * cs.x - x2 * cs.y), o2 = f2bf(x2 * cs.x + x1 * cs.y);
; #pragma unroll
;           for (int hh = 0; hh < 8; ++hh) {
;             bf16* kp = Kb + ((size_t)(bidx * 8 + hh) * 2048 + s) * 192 + 128;
;             kp[r] = o1; kp[32 + r] = o2;
;           }
;         }
	v_lshl_add_u64 v[70:71], v[70:71], 3, s[10:11]
	v_mov_b32_e32 v70, v194
	v_mov_b32_e32 v71, v195
	v_mul_f32_e32 v69, v58, v71
	v_fmac_f32_e32 v69, v42, v70
	v_mul_f32_e32 v67, v42, v71
	v_cvt_pk_bf16_f32 v74, v69, s0
	v_ashrrev_i32_e32 v69, 31, v68
	v_fma_f32 v67, v58, v70, -v67
	v_lshl_add_u64 v[70:71], s[38:39], 0, v[68:69]
	v_cvt_pk_bf16_f32 v67, v67, s0
	v_mad_u64_u32 v[72:73], s[0:1], v70, s53, v[64:65]
	v_mad_i32_i24 v73, v71, s53, v73
	v_lshl_add_u64 v[70:71], v[72:73], 0, v[134:135]
	v_lshl_add_u64 v[72:73], v[70:71], 0, s[12:13]
	v_add_co_u32_e32 v70, vcc, s54, v70
	s_nop 1
	v_addc_co_u32_e32 v71, vcc, 0, v71, vcc
	global_store_short v[70:71], v67, off offset:256
	global_store_short v[72:73], v74, off offset:64
	v_lshl_add_u64 v[70:71], s[34:35], 0, v[68:69]
	v_mad_u64_u32 v[72:73], s[0:1], v70, s53, v[64:65]
	v_mad_i32_i24 v73, v71, s53, v73
	v_lshl_add_u64 v[70:71], v[72:73], 0, v[134:135]
	v_lshl_add_u64 v[72:73], v[70:71], 0, s[12:13]
	v_add_co_u32_e32 v70, vcc, s54, v70
	s_nop 1
	v_addc_co_u32_e32 v71, vcc, 0, v71, vcc
	global_store_short v[70:71], v67, off offset:256
	global_store_short v[72:73], v74, off offset:64
	v_lshl_add_u64 v[70:71], s[30:31], 0, v[68:69]
	v_mad_u64_u32 v[72:73], s[0:1], v70, s53, v[64:65]
	v_mad_i32_i24 v73, v71, s53, v73
	v_lshl_add_u64 v[70:71], v[72:73], 0, v[134:135]
	v_lshl_add_u64 v[72:73], v[70:71], 0, s[12:13]
	v_add_co_u32_e32 v70, vcc, s54, v70
	s_nop 1
	v_addc_co_u32_e32 v71, vcc, 0, v71, vcc
	global_store_short v[70:71], v67, off offset:256
	global_store_short v[72:73], v74, off offset:64
	v_lshl_add_u64 v[70:71], s[20:21], 0, v[68:69]
	v_mad_u64_u32 v[72:73], s[0:1], v70, s53, v[64:65]
	v_mad_i32_i24 v73, v71, s53, v73
	v_lshl_add_u64 v[70:71], v[72:73], 0, v[134:135]
	v_lshl_add_u64 v[72:73], v[70:71], 0, s[12:13]
	v_add_co_u32_e32 v70, vcc, s54, v70
	s_nop 1
	v_addc_co_u32_e32 v71, vcc, 0, v71, vcc
	global_store_short v[70:71], v67, off offset:256
	global_store_short v[72:73], v74, off offset:64
	v_lshl_add_u64 v[70:71], s[18:19], 0, v[68:69]
	v_mad_u64_u32 v[72:73], s[0:1], v70, s53, v[64:65]
	v_mad_i32_i24 v73, v71, s53, v73
	v_lshl_add_u64 v[70:71], v[72:73], 0, v[134:135]
	v_lshl_add_u64 v[72:73], v[70:71], 0, s[12:13]
	v_add_co_u32_e32 v70, vcc, s54, v70
	s_nop 1
	v_addc_co_u32_e32 v71, vcc, 0, v71, vcc
	global_store_short v[70:71], v67, off offset:256
	global_store_short v[72:73], v74, off offset:64
	v_lshl_add_u64 v[70:71], s[40:41], 0, v[68:69]
	v_mad_u64_u32 v[72:73], s[0:1], v70, s53, v[64:65]
	v_mad_i32_i24 v73, v71, s53, v73
	v_lshl_add_u64 v[70:71], v[72:73], 0, v[134:135]
	v_lshl_add_u64 v[72:73], v[70:71], 0, s[12:13]
	v_add_co_u32_e32 v70, vcc, s54, v70
	s_nop 1
	v_addc_co_u32_e32 v71, vcc, 0, v71, vcc
	global_store_short v[70:71], v67, off offset:256
	global_store_short v[72:73], v74, off offset:64
	v_lshl_add_u64 v[70:71], s[42:43], 0, v[68:69]
	v_mad_u64_u32 v[72:73], s[0:1], v70, s53, v[64:65]
	v_mad_i32_i24 v73, v71, s53, v73
	v_lshl_add_u64 v[70:71], v[72:73], 0, v[134:135]
	v_lshl_add_u64 v[72:73], v[70:71], 0, s[12:13]
	v_add_co_u32_e32 v70, vcc, s54, v70
	v_lshl_add_u64 v[68:69], s[44:45], 0, v[68:69]
	s_nop 0
	v_addc_co_u32_e32 v71, vcc, 0, v71, vcc
	global_store_short v[70:71], v67, off offset:256
	global_store_short v[72:73], v74, off offset:64
	v_mad_u64_u32 v[70:71], s[0:1], v68, s53, v[64:65]
	v_mad_i32_i24 v71, v69, s53, v71
	v_lshl_add_u64 v[68:69], v[70:71], 0, v[134:135]
	v_lshl_add_u64 v[70:71], v[68:69], 0, s[12:13]
	v_add_co_u32_e32 v68, vcc, s54, v68
	s_nop 1
	v_addc_co_u32_e32 v69, vcc, 0, v69, vcc
	global_store_short v[68:69], v67, off offset:256
	global_store_short v[70:71], v74, off offset:64
	v_or_b32_e32 v68, 19, v66
	v_lshl_or_b32 v70, v68, 5, v128
	v_ashrrev_i32_e32 v71, 31, v70
	v_lshl_add_u64 v[70:71], v[70:71], 3, s[10:11]
	v_mov_b32_e32 v70, v196
	v_mov_b32_e32 v71, v197
	v_mul_f32_e32 v69, v59, v71
	v_fmac_f32_e32 v69, v43, v70
	v_mul_f32_e32 v67, v43, v71
	v_cvt_pk_bf16_f32 v74, v69, s0
	v_ashrrev_i32_e32 v69, 31, v68
	v_fma_f32 v67, v59, v70, -v67
	v_lshl_add_u64 v[70:71], s[38:39], 0, v[68:69]
	v_cvt_pk_bf16_f32 v67, v67, s0
	v_mad_u64_u32 v[72:73], s[0:1], v70, s53, v[64:65]
	v_mad_i32_i24 v73, v71, s53, v73
	v_lshl_add_u64 v[70:71], v[72:73], 0, v[134:135]
	v_lshl_add_u64 v[72:73], v[70:71], 0, s[12:13]
	v_add_co_u32_e32 v70, vcc, s54, v70
	s_nop 1
	v_addc_co_u32_e32 v71, vcc, 0, v71, vcc
	global_store_short v[70:71], v67, off offset:256
	global_store_short v[72:73], v74, off offset:64
	v_lshl_add_u64 v[70:71], s[34:35], 0, v[68:69]
	v_mad_u64_u32 v[72:73], s[0:1], v70, s53, v[64:65]
	v_mad_i32_i24 v73, v71, s53, v73
	v_lshl_add_u64 v[70:71], v[72:73], 0, v[134:135]
	v_lshl_add_u64 v[72:73], v[70:71], 0, s[12:13]
	v_add_co_u32_e32 v70, vcc, s54, v70
	s_nop 1
	v_addc_co_u32_e32 v71, vcc, 0, v71, vcc
	global_store_short v[70:71], v67, off offset:256
	global_store_short v[72:73], v74, off offset:64
	v_lshl_add_u64 v[70:71], s[30:31], 0, v[68:69]
	v_mad_u64_u32 v[72:73], s[0:1], v70, s53, v[64:65]
	v_mad_i32_i24 v73, v71, s53, v73
	v_lshl_add_u64 v[70:71], v[72:73], 0, v[134:135]
	v_lshl_add_u64 v[72:73], v[70:71], 0, s[12:13]
	v_add_co_u32_e32 v70, vcc, s54, v70
	s_nop 1
	v_addc_co_u32_e32 v71, vcc, 0, v71, vcc
	global_store_short v[70:71], v67, off offset:256
	global_store_short v[72:73], v74, off offset:64
	v_lshl_add_u64 v[70:71], s[20:21], 0, v[68:69]
	v_mad_u64_u32 v[72:73], s[0:1], v70, s53, v[64:65]
	v_mad_i32_i24 v73, v71, s53, v73
	v_lshl_add_u64 v[70:71], v[72:73], 0, v[134:135]
	v_lshl_add_u64 v[72:73], v[70:71], 0, s[12:13]
	v_add_co_u32_e32 v70, vcc, s54, v70
	s_nop 1
	v_addc_co_u32_e32 v71, vcc, 0, v71, vcc
; DI bf16 f2bf(float a) { return (bf16)(pack2(a, 0.f) & 0xffffu); }
; DI int crow(int i, int g) { return (i & 3) + 8 * (i >> 2) + 4 * g; }
;     ...
;         const float2* t64 = (const float2*)(ws + OFF_TAB64);
;         bf16* Kb = (bf16*)(ws + OFF_K);
; #pragma unroll
;         for (int i = 0; i < 16; ++i) {
;           int s = s0 + crow(i, g);
;           float2 cs = t64[s * 32 + r];
;           float x1 = acc[0][i], x2 = acc[1][i];
;           bf16 o1 = f2bf(x1 * cs.x - x2 * cs.y), o2 = f2bf(x2 * cs.x + x1 * cs.y);
; #pragma unroll
;           for (int hh = 0; hh < 8; ++hh) {
;             bf16* kp = Kb + ((size_t)(bidx * 8 + hh) * 2048 + s) * 192 + 128;
;             kp[r] = o1; kp[32 + r] = o2;
;           }
;         }
	global_store_short v[70:71], v67, off offset:256
	global_store_short v[72:73], v74, off offset:64
	v_lshl_add_u64 v[70:71], s[18:19], 0, v[68:69]
	v_mad_u64_u32 v[72:73], s[0:1], v70, s53, v[64:65]
	v_mad_i32_i24 v73, v71, s53, v73
	v_lshl_add_u64 v[70:71], v[72:73], 0, v[134:135]
	v_lshl_add_u64 v[72:73], v[70:71], 0, s[12:13]
	v_add_co_u32_e32 v70, vcc, s54, v70
	s_nop 1
	v_addc_co_u32_e32 v71, vcc, 0, v71, vcc
	global_store_short v[70:71], v67, off offset:256
	global_store_short v[72:73], v74, off offset:64
	v_lshl_add_u64 v[70:71], s[40:41], 0, v[68:69]
	v_mad_u64_u32 v[72:73], s[0:1], v70, s53, v[64:65]
	v_mad_i32_i24 v73, v71, s53, v73
	v_lshl_add_u64 v[70:71], v[72:73], 0, v[134:135]
	v_lshl_add_u64 v[72:73], v[70:71], 0, s[12:13]
	v_add_co_u32_e32 v70, vcc, s54, v70
	s_nop 1
	v_addc_co_u32_e32 v71, vcc, 0, v71, vcc
	global_store_short v[70:71], v67, off offset:256
	global_store_short v[72:73], v74, off offset:64
	v_lshl_add_u64 v[70:71], s[42:43], 0, v[68:69]
	v_mad_u64_u32 v[72:73], s[0:1], v70, s53, v[64:65]
	v_mad_i32_i24 v73, v71, s53, v73
	v_lshl_add_u64 v[70:71], v[72:73], 0, v[134:135]
	v_lshl_add_u64 v[72:73], v[70:71], 0, s[12:13]
	v_add_co_u32_e32 v70, vcc, s54, v70
	v_lshl_add_u64 v[68:69], s[44:45], 0, v[68:69]
	s_nop 0
	v_addc_co_u32_e32 v71, vcc, 0, v71, vcc
	global_store_short v[70:71], v67, off offset:256
	global_store_short v[72:73], v74, off offset:64
	v_mad_u64_u32 v[70:71], s[0:1], v68, s53, v[64:65]
	v_mad_i32_i24 v71, v69, s53, v71
	v_lshl_add_u64 v[68:69], v[70:71], 0, v[134:135]
	v_lshl_add_u64 v[70:71], v[68:69], 0, s[12:13]
	v_add_co_u32_e32 v68, vcc, s54, v68
	s_nop 1
	v_addc_co_u32_e32 v69, vcc, 0, v69, vcc
	global_store_short v[68:69], v67, off offset:256
	global_store_short v[70:71], v74, off offset:64
	v_or_b32_e32 v68, 24, v66
	v_lshl_or_b32 v70, v68, 5, v128
	v_ashrrev_i32_e32 v71, 31, v70
	v_lshl_add_u64 v[70:71], v[70:71], 3, s[10:11]
	v_mov_b32_e32 v70, v198
	v_mov_b32_e32 v71, v199
	v_mul_f32_e32 v69, v60, v71
	v_fmac_f32_e32 v69, v44, v70
	v_mul_f32_e32 v67, v44, v71
	v_cvt_pk_bf16_f32 v74, v69, s0
	v_ashrrev_i32_e32 v69, 31, v68
	v_fma_f32 v67, v60, v70, -v67
	v_lshl_add_u64 v[70:71], s[38:39], 0, v[68:69]
	v_cvt_pk_bf16_f32 v67, v67, s0
	v_mad_u64_u32 v[72:73], s[0:1], v70, s53, v[64:65]
	v_mad_i32_i24 v73, v71, s53, v73
	v_lshl_add_u64 v[70:71], v[72:73], 0, v[134:135]
	v_lshl_add_u64 v[72:73], v[70:71], 0, s[12:13]
	v_add_co_u32_e32 v70, vcc, s54, v70
	s_nop 1
	v_addc_co_u32_e32 v71, vcc, 0, v71, vcc
	global_store_short v[70:71], v67, off offset:256
	global_store_short v[72:73], v74, off offset:64
	v_lshl_add_u64 v[70:71], s[34:35], 0, v[68:69]
	v_mad_u64_u32 v[72:73], s[0:1], v70, s53, v[64:65]
	v_mad_i32_i24 v73, v71, s53, v73
	v_lshl_add_u64 v[70:71], v[72:73], 0, v[134:135]
	v_lshl_add_u64 v[72:73], v[70:71], 0, s[12:13]
	v_add_co_u32_e32 v70, vcc, s54, v70
	s_nop 1
	v_addc_co_u32_e32 v71, vcc, 0, v71, vcc
	global_store_short v[70:71], v67, off offset:256
	global_store_short v[72:73], v74, off offset:64
	v_lshl_add_u64 v[70:71], s[30:31], 0, v[68:69]
	v_mad_u64_u32 v[72:73], s[0:1], v70, s53, v[64:65]
	v_mad_i32_i24 v73, v71, s53, v73
	v_lshl_add_u64 v[70:71], v[72:73], 0, v[134:135]
	v_lshl_add_u64 v[72:73], v[70:71], 0, s[12:13]
	v_add_co_u32_e32 v70, vcc, s54, v70
	s_nop 1
	v_addc_co_u32_e32 v71, vcc, 0, v71, vcc
	global_store_short v[70:71], v67, off offset:256
	global_store_short v[72:73], v74, off offset:64
	v_lshl_add_u64 v[70:71], s[20:21], 0, v[68:69]
	v_mad_u64_u32 v[72:73], s[0:1], v70, s53, v[64:65]
	v_mad_i32_i24 v73, v71, s53, v73
	v_lshl_add_u64 v[70:71], v[72:73], 0, v[134:135]
	v_lshl_add_u64 v[72:73], v[70:71], 0, s[12:13]
	v_add_co_u32_e32 v70, vcc, s54, v70
	s_nop 1
	v_addc_co_u32_e32 v71, vcc, 0, v71, vcc
	global_store_short v[70:71], v67, off offset:256
	global_store_short v[72:73], v74, off offset:64
	v_lshl_add_u64 v[70:71], s[18:19], 0, v[68:69]
	v_mad_u64_u32 v[72:73], s[0:1], v70, s53, v[64:65]
	v_mad_i32_i24 v73, v71, s53, v73
	v_lshl_add_u64 v[70:71], v[72:73], 0, v[134:135]
	v_lshl_add_u64 v[72:73], v[70:71], 0, s[12:13]
	v_add_co_u32_e32 v70, vcc, s54, v70
	s_nop 1
	v_addc_co_u32_e32 v71, vcc, 0, v71, vcc
	global_store_short v[70:71], v67, off offset:256
	global_store_short v[72:73], v74, off offset:64
	v_lshl_add_u64 v[70:71], s[40:41], 0, v[68:69]
	v_mad_u64_u32 v[72:73], s[0:1], v70, s53, v[64:65]
	v_mad_i32_i24 v73, v71, s53, v73
	v_lshl_add_u64 v[70:71], v[72:73], 0, v[134:135]
	v_lshl_add_u64 v[72:73], v[70:71], 0, s[12:13]
	v_add_co_u32_e32 v70, vcc, s54, v70
	s_nop 1
	v_addc_co_u32_e32 v71, vcc, 0, v71, vcc
	global_store_short v[70:71], v67, off offset:256
	global_store_short v[72:73], v74, off offset:64
	v_lshl_add_u64 v[70:71], s[42:43], 0, v[68:69]
	v_mad_u64_u32 v[72:73], s[0:1], v70, s53, v[64:65]
	v_mad_i32_i24 v73, v71, s53, v73
	v_lshl_add_u64 v[70:71], v[72:73], 0, v[134:135]
	v_lshl_add_u64 v[72:73], v[70:71], 0, s[12:13]
	v_add_co_u32_e32 v70, vcc, s54, v70
	v_lshl_add_u64 v[68:69], s[44:45], 0, v[68:69]
	s_nop 0
	v_addc_co_u32_e32 v71, vcc, 0, v71, vcc
	global_store_short v[70:71], v67, off offset:256
	global_store_short v[72:73], v74, off offset:64
	v_mad_u64_u32 v[70:71], s[0:1], v68, s53, v[64:65]
	v_mad_i32_i24 v71, v69, s53, v71
	v_lshl_add_u64 v[68:69], v[70:71], 0, v[134:135]
	v_lshl_add_u64 v[70:71], v[68:69], 0, s[12:13]
	v_add_co_u32_e32 v68, vcc, s54, v68
	s_nop 1
	v_addc_co_u32_e32 v69, vcc, 0, v69, vcc
	global_store_short v[68:69], v67, off offset:256
	global_store_short v[70:71], v74, off offset:64
	v_or_b32_e32 v68, 25, v66
	v_lshl_or_b32 v70, v68, 5, v128
	v_ashrrev_i32_e32 v71, 31, v70
	v_lshl_add_u64 v[70:71], v[70:71], 3, s[10:11]
; DI bf16 f2bf(float a) { return (bf16)(pack2(a, 0.f) & 0xffffu); }
; DI int crow(int i, int g) { return (i & 3) + 8 * (i >> 2) + 4 * g; }
;     ...
;         const float2* t64 = (const float2*)(ws + OFF_TAB64);
;         bf16* Kb = (bf16*)(ws + OFF_K);
; #pragma unroll
;         for (int i = 0; i < 16; ++i) {
;           int s = s0 + crow(i, g);
;           float2 cs = t64[s * 32 + r];
;           float x1 = acc[0][i], x2 = acc[1][i];
;           bf16 o1 = f2bf(x1 * cs.x - x2 * cs.y), o2 = f2bf(x2 * cs.x + x1 * cs.y);
; #pragma unroll
;           for (int hh = 0; hh < 8; ++hh) {
;             bf16* kp = Kb + ((size_t)(bidx * 8 + hh) * 2048 + s) * 192 + 128;
;             kp[r] = o1; kp[32 + r] = o2;
;           }
;         }
	v_mov_b32_e32 v70, v200
	v_mov_b32_e32 v71, v201
	v_mul_f32_e32 v69, v61, v71
	v_fmac_f32_e32 v69, v45, v70
	v_mul_f32_e32 v67, v45, v71
	v_cvt_pk_bf16_f32 v74, v69, s0
	v_ashrrev_i32_e32 v69, 31, v68
	v_fma_f32 v67, v61, v70, -v67
	v_lshl_add_u64 v[70:71], s[38:39], 0, v[68:69]
	v_cvt_pk_bf16_f32 v67, v67, s0
	v_mad_u64_u32 v[72:73], s[0:1], v70, s53, v[64:65]
	v_mad_i32_i24 v73, v71, s53, v73
	v_lshl_add_u64 v[70:71], v[72:73], 0, v[134:135]
	v_lshl_add_u64 v[72:73], v[70:71], 0, s[12:13]
	v_add_co_u32_e32 v70, vcc, s54, v70
	s_nop 1
	v_addc_co_u32_e32 v71, vcc, 0, v71, vcc
	global_store_short v[70:71], v67, off offset:256
	global_store_short v[72:73], v74, off offset:64
	v_lshl_add_u64 v[70:71], s[34:35], 0, v[68:69]
	v_mad_u64_u32 v[72:73], s[0:1], v70, s53, v[64:65]
	v_mad_i32_i24 v73, v71, s53, v73
	v_lshl_add_u64 v[70:71], v[72:73], 0, v[134:135]
	v_lshl_add_u64 v[72:73], v[70:71], 0, s[12:13]
	v_add_co_u32_e32 v70, vcc, s54, v70
	s_nop 1
	v_addc_co_u32_e32 v71, vcc, 0, v71, vcc
	global_store_short v[70:71], v67, off offset:256
	global_store_short v[72:73], v74, off offset:64
	v_lshl_add_u64 v[70:71], s[30:31], 0, v[68:69]
	v_mad_u64_u32 v[72:73], s[0:1], v70, s53, v[64:65]
	v_mad_i32_i24 v73, v71, s53, v73
	v_lshl_add_u64 v[70:71], v[72:73], 0, v[134:135]
	v_lshl_add_u64 v[72:73], v[70:71], 0, s[12:13]
	v_add_co_u32_e32 v70, vcc, s54, v70
	s_nop 1
	v_addc_co_u32_e32 v71, vcc, 0, v71, vcc
	global_store_short v[70:71], v67, off offset:256
	global_store_short v[72:73], v74, off offset:64
	v_lshl_add_u64 v[70:71], s[20:21], 0, v[68:69]
	v_mad_u64_u32 v[72:73], s[0:1], v70, s53, v[64:65]
	v_mad_i32_i24 v73, v71, s53, v73
	v_lshl_add_u64 v[70:71], v[72:73], 0, v[134:135]
	v_lshl_add_u64 v[72:73], v[70:71], 0, s[12:13]
	v_add_co_u32_e32 v70, vcc, s54, v70
	s_nop 1
	v_addc_co_u32_e32 v71, vcc, 0, v71, vcc
	global_store_short v[70:71], v67, off offset:256
	global_store_short v[72:73], v74, off offset:64
	v_lshl_add_u64 v[70:71], s[18:19], 0, v[68:69]
	v_mad_u64_u32 v[72:73], s[0:1], v70, s53, v[64:65]
	v_mad_i32_i24 v73, v71, s53, v73
	v_lshl_add_u64 v[70:71], v[72:73], 0, v[134:135]
	v_lshl_add_u64 v[72:73], v[70:71], 0, s[12:13]
	v_add_co_u32_e32 v70, vcc, s54, v70
	s_nop 1
	v_addc_co_u32_e32 v71, vcc, 0, v71, vcc
	global_store_short v[70:71], v67, off offset:256
	global_store_short v[72:73], v74, off offset:64
	v_lshl_add_u64 v[70:71], s[40:41], 0, v[68:69]
	v_mad_u64_u32 v[72:73], s[0:1], v70, s53, v[64:65]
	v_mad_i32_i24 v73, v71, s53, v73
	v_lshl_add_u64 v[70:71], v[72:73], 0, v[134:135]
	v_lshl_add_u64 v[72:73], v[70:71], 0, s[12:13]
	v_add_co_u32_e32 v70, vcc, s54, v70
	s_nop 1
	v_addc_co_u32_e32 v71, vcc, 0, v71, vcc
	global_store_short v[70:71], v67, off offset:256
	global_store_short v[72:73], v74, off offset:64
	v_lshl_add_u64 v[70:71], s[42:43], 0, v[68:69]
	v_mad_u64_u32 v[72:73], s[0:1], v70, s53, v[64:65]
	v_mad_i32_i24 v73, v71, s53, v73
	v_lshl_add_u64 v[70:71], v[72:73], 0, v[134:135]
	v_lshl_add_u64 v[72:73], v[70:71], 0, s[12:13]
	v_add_co_u32_e32 v70, vcc, s54, v70
	v_lshl_add_u64 v[68:69], s[44:45], 0, v[68:69]
	s_nop 0
	v_addc_co_u32_e32 v71, vcc, 0, v71, vcc
	global_store_short v[70:71], v67, off offset:256
	global_store_short v[72:73], v74, off offset:64
	v_mad_u64_u32 v[70:71], s[0:1], v68, s53, v[64:65]
	v_mad_i32_i24 v71, v69, s53, v71
	v_lshl_add_u64 v[68:69], v[70:71], 0, v[134:135]
	v_lshl_add_u64 v[70:71], v[68:69], 0, s[12:13]
	v_add_co_u32_e32 v68, vcc, s54, v68
	s_nop 1
	v_addc_co_u32_e32 v69, vcc, 0, v69, vcc
	global_store_short v[68:69], v67, off offset:256
	global_store_short v[70:71], v74, off offset:64
	v_or_b32_e32 v68, 26, v66
	v_lshl_or_b32 v70, v68, 5, v128
	v_ashrrev_i32_e32 v71, 31, v70
	v_lshl_add_u64 v[70:71], v[70:71], 3, s[10:11]
	v_mov_b32_e32 v70, v202
	v_mov_b32_e32 v71, v203
	v_or_b32_e32 v66, 27, v66
	v_mul_f32_e32 v69, v62, v71
	v_fmac_f32_e32 v69, v46, v70
	v_mul_f32_e32 v67, v46, v71
	v_cvt_pk_bf16_f32 v74, v69, s0
	v_ashrrev_i32_e32 v69, 31, v68
	v_fma_f32 v67, v62, v70, -v67
	v_lshl_add_u64 v[70:71], s[38:39], 0, v[68:69]
	v_cvt_pk_bf16_f32 v67, v67, s0
	v_mad_u64_u32 v[72:73], s[0:1], v70, s53, v[64:65]
	v_mad_i32_i24 v73, v71, s53, v73
	v_lshl_add_u64 v[70:71], v[72:73], 0, v[134:135]
	v_lshl_add_u64 v[72:73], v[70:71], 0, s[12:13]
	v_add_co_u32_e32 v70, vcc, s54, v70
	s_nop 1
	v_addc_co_u32_e32 v71, vcc, 0, v71, vcc
	global_store_short v[70:71], v67, off offset:256
	global_store_short v[72:73], v74, off offset:64
	v_lshl_add_u64 v[70:71], s[34:35], 0, v[68:69]
	v_mad_u64_u32 v[72:73], s[0:1], v70, s53, v[64:65]
	v_mad_i32_i24 v73, v71, s53, v73
	v_lshl_add_u64 v[70:71], v[72:73], 0, v[134:135]
	v_lshl_add_u64 v[72:73], v[70:71], 0, s[12:13]
	v_add_co_u32_e32 v70, vcc, s54, v70
	s_nop 1
	v_addc_co_u32_e32 v71, vcc, 0, v71, vcc
	global_store_short v[70:71], v67, off offset:256
	global_store_short v[72:73], v74, off offset:64
	v_lshl_add_u64 v[70:71], s[30:31], 0, v[68:69]
	v_mad_u64_u32 v[72:73], s[0:1], v70, s53, v[64:65]
	v_mad_i32_i24 v73, v71, s53, v73
	v_lshl_add_u64 v[70:71], v[72:73], 0, v[134:135]
	v_lshl_add_u64 v[72:73], v[70:71], 0, s[12:13]
	v_add_co_u32_e32 v70, vcc, s54, v70
	s_nop 1
	v_addc_co_u32_e32 v71, vcc, 0, v71, vcc
	global_store_short v[70:71], v67, off offset:256
	global_store_short v[72:73], v74, off offset:64
	v_lshl_add_u64 v[70:71], s[20:21], 0, v[68:69]
	v_mad_u64_u32 v[72:73], s[0:1], v70, s53, v[64:65]
	v_mad_i32_i24 v73, v71, s53, v73
	v_lshl_add_u64 v[70:71], v[72:73], 0, v[134:135]
	v_lshl_add_u64 v[72:73], v[70:71], 0, s[12:13]
	v_add_co_u32_e32 v70, vcc, s54, v70
; DI bf16 f2bf(float a) { return (bf16)(pack2(a, 0.f) & 0xffffu); }
; DI int crow(int i, int g) { return (i & 3) + 8 * (i >> 2) + 4 * g; }
;     ...
;         const float2* t64 = (const float2*)(ws + OFF_TAB64);
;         bf16* Kb = (bf16*)(ws + OFF_K);
; #pragma unroll
;         for (int i = 0; i < 16; ++i) {
;           int s = s0 + crow(i, g);
;           float2 cs = t64[s * 32 + r];
;           float x1 = acc[0][i], x2 = acc[1][i];
;           bf16 o1 = f2bf(x1 * cs.x - x2 * cs.y), o2 = f2bf(x2 * cs.x + x1 * cs.y);
; #pragma unroll
;           for (int hh = 0; hh < 8; ++hh) {
;             bf16* kp = Kb + ((size_t)(bidx * 8 + hh) * 2048 + s) * 192 + 128;
;             kp[r] = o1; kp[32 + r] = o2;
;           }
;         }
	s_nop 1
	v_addc_co_u32_e32 v71, vcc, 0, v71, vcc
	global_store_short v[70:71], v67, off offset:256
	global_store_short v[72:73], v74, off offset:64
	v_lshl_add_u64 v[70:71], s[18:19], 0, v[68:69]
	v_mad_u64_u32 v[72:73], s[0:1], v70, s53, v[64:65]
	v_mad_i32_i24 v73, v71, s53, v73
	v_lshl_add_u64 v[70:71], v[72:73], 0, v[134:135]
	v_lshl_add_u64 v[72:73], v[70:71], 0, s[12:13]
	v_add_co_u32_e32 v70, vcc, s54, v70
	s_nop 1
	v_addc_co_u32_e32 v71, vcc, 0, v71, vcc
	global_store_short v[70:71], v67, off offset:256
	global_store_short v[72:73], v74, off offset:64
	v_lshl_add_u64 v[70:71], s[40:41], 0, v[68:69]
	v_mad_u64_u32 v[72:73], s[0:1], v70, s53, v[64:65]
	v_mad_i32_i24 v73, v71, s53, v73
	v_lshl_add_u64 v[70:71], v[72:73], 0, v[134:135]
	v_lshl_add_u64 v[72:73], v[70:71], 0, s[12:13]
	v_add_co_u32_e32 v70, vcc, s54, v70
	s_nop 1
	v_addc_co_u32_e32 v71, vcc, 0, v71, vcc
	global_store_short v[70:71], v67, off offset:256
	global_store_short v[72:73], v74, off offset:64
	v_lshl_add_u64 v[70:71], s[42:43], 0, v[68:69]
	v_mad_u64_u32 v[72:73], s[0:1], v70, s53, v[64:65]
	v_mad_i32_i24 v73, v71, s53, v73
	v_lshl_add_u64 v[70:71], v[72:73], 0, v[134:135]
	v_lshl_add_u64 v[72:73], v[70:71], 0, s[12:13]
	v_add_co_u32_e32 v70, vcc, s54, v70
	v_lshl_add_u64 v[68:69], s[44:45], 0, v[68:69]
	s_nop 0
	v_addc_co_u32_e32 v71, vcc, 0, v71, vcc
	global_store_short v[70:71], v67, off offset:256
	global_store_short v[72:73], v74, off offset:64
	v_mad_u64_u32 v[70:71], s[0:1], v68, s53, v[64:65]
	v_mad_i32_i24 v71, v69, s53, v71
	v_lshl_add_u64 v[68:69], v[70:71], 0, v[134:135]
	v_lshl_add_u64 v[70:71], v[68:69], 0, s[12:13]
	v_add_co_u32_e32 v68, vcc, s54, v68
	s_nop 1
	v_addc_co_u32_e32 v69, vcc, 0, v69, vcc
	global_store_short v[68:69], v67, off offset:256
	global_store_short v[70:71], v74, off offset:64
	v_lshl_or_b32 v68, v66, 5, v128
	v_ashrrev_i32_e32 v69, 31, v68
	v_lshl_add_u64 v[68:69], v[68:69], 3, s[10:11]
	v_mov_b32_e32 v68, v204
	v_mov_b32_e32 v69, v205
	v_mul_f32_e32 v67, v47, v69
	v_fma_f32 v67, v63, v68, -v67
	v_cvt_pk_bf16_f32 v72, v67, s0
	v_mul_f32_e32 v67, v63, v69
	v_fmac_f32_e32 v67, v47, v68
	v_cvt_pk_bf16_f32 v73, v67, s0
	v_ashrrev_i32_e32 v67, 31, v66
	v_lshl_add_u64 v[68:69], s[38:39], 0, v[66:67]
	v_mad_u64_u32 v[70:71], s[0:1], v68, s53, v[64:65]
	v_mad_i32_i24 v71, v69, s53, v71
	v_lshl_add_u64 v[68:69], v[70:71], 0, v[134:135]
	v_lshl_add_u64 v[70:71], v[68:69], 0, s[12:13]
	v_add_co_u32_e32 v68, vcc, s54, v68
	s_nop 1
	v_addc_co_u32_e32 v69, vcc, 0, v69, vcc
	global_store_short v[68:69], v72, off offset:256
	global_store_short v[70:71], v73, off offset:64
	v_lshl_add_u64 v[68:69], s[34:35], 0, v[66:67]
	v_mad_u64_u32 v[70:71], s[0:1], v68, s53, v[64:65]
	v_mad_i32_i24 v71, v69, s53, v71
	v_lshl_add_u64 v[68:69], v[70:71], 0, v[134:135]
	v_lshl_add_u64 v[70:71], v[68:69], 0, s[12:13]
	v_add_co_u32_e32 v68, vcc, s54, v68
	s_nop 1
	v_addc_co_u32_e32 v69, vcc, 0, v69, vcc
	global_store_short v[68:69], v72, off offset:256
	global_store_short v[70:71], v73, off offset:64
	v_lshl_add_u64 v[68:69], s[30:31], 0, v[66:67]
	v_mad_u64_u32 v[70:71], s[0:1], v68, s53, v[64:65]
	v_mad_i32_i24 v71, v69, s53, v71
	v_lshl_add_u64 v[68:69], v[70:71], 0, v[134:135]
	v_lshl_add_u64 v[70:71], v[68:69], 0, s[12:13]
	v_add_co_u32_e32 v68, vcc, s54, v68
	s_nop 1
	v_addc_co_u32_e32 v69, vcc, 0, v69, vcc
	global_store_short v[68:69], v72, off offset:256
	global_store_short v[70:71], v73, off offset:64
	v_lshl_add_u64 v[68:69], s[20:21], 0, v[66:67]
	v_mad_u64_u32 v[70:71], s[0:1], v68, s53, v[64:65]
	v_mad_i32_i24 v71, v69, s53, v71
	v_lshl_add_u64 v[68:69], v[70:71], 0, v[134:135]
	v_lshl_add_u64 v[70:71], v[68:69], 0, s[12:13]
	v_add_co_u32_e32 v68, vcc, s54, v68
	s_nop 1
	v_addc_co_u32_e32 v69, vcc, 0, v69, vcc
	global_store_short v[68:69], v72, off offset:256
	global_store_short v[70:71], v73, off offset:64
	v_lshl_add_u64 v[68:69], s[18:19], 0, v[66:67]
	v_mad_u64_u32 v[70:71], s[0:1], v68, s53, v[64:65]
	v_mad_i32_i24 v71, v69, s53, v71
	v_lshl_add_u64 v[68:69], v[70:71], 0, v[134:135]
	v_lshl_add_u64 v[70:71], v[68:69], 0, s[12:13]
	v_add_co_u32_e32 v68, vcc, s54, v68
	s_nop 1
	v_addc_co_u32_e32 v69, vcc, 0, v69, vcc
	global_store_short v[68:69], v72, off offset:256
	global_store_short v[70:71], v73, off offset:64
	v_lshl_add_u64 v[68:69], s[40:41], 0, v[66:67]
	v_mad_u64_u32 v[70:71], s[0:1], v68, s53, v[64:65]
	v_mad_i32_i24 v71, v69, s53, v71
	v_lshl_add_u64 v[68:69], v[70:71], 0, v[134:135]
	v_lshl_add_u64 v[70:71], v[68:69], 0, s[12:13]
	v_add_co_u32_e32 v68, vcc, s54, v68
	s_nop 1
	v_addc_co_u32_e32 v69, vcc, 0, v69, vcc
	global_store_short v[68:69], v72, off offset:256
	global_store_short v[70:71], v73, off offset:64
	v_lshl_add_u64 v[68:69], s[42:43], 0, v[66:67]
	v_mad_u64_u32 v[70:71], s[0:1], v68, s53, v[64:65]
	v_mad_i32_i24 v71, v69, s53, v71
	v_lshl_add_u64 v[66:67], s[44:45], 0, v[66:67]
	v_lshl_add_u64 v[68:69], v[70:71], 0, v[134:135]
	v_mad_u64_u32 v[64:65], s[0:1], v66, s53, v[64:65]
	v_lshl_add_u64 v[70:71], v[68:69], 0, s[12:13]
	v_add_co_u32_e32 v68, vcc, s54, v68
	v_mad_i32_i24 v65, v67, s53, v65
	s_nop 0
	v_addc_co_u32_e32 v69, vcc, 0, v69, vcc
	v_lshl_add_u64 v[64:65], v[64:65], 0, v[134:135]
	v_lshl_add_u64 v[66:67], v[64:65], 0, s[12:13]
	v_add_co_u32_e32 v64, vcc, 0x13000000, v64
	global_store_short v[68:69], v72, off offset:256
	global_store_short v[70:71], v73, off offset:64
	v_addc_co_u32_e32 v65, vcc, 0, v65, vcc
	global_store_short v[64:65], v72, off offset:256
	global_store_short v[66:67], v73, off offset:64
	s_cbranch_execnz .LBB0_226
